# hand-written row-op phases (pb+2, pb+8, pb+11) with all row loads issued up front and DPP wave reductions
# speedup vs baseline: 1.1884x; 1.0178x over previous
.LBB0_319:
	s_andn2_b64 vcc, exec, s[2:3]
	s_cbranch_vccnz .LBB0_373
	v_readlane_b32 s10, v164, 0
	v_readlane_b32 s11, v162, 14
	v_lshrrev_b32_e32 v80, 6, v128
	v_and_b32_e32 v81, 63, v128
	v_readlane_b32 s16, v163, 13
	v_readlane_b32 s17, v163, 14
	v_readlane_b32 s18, v163, 15
	v_readlane_b32 s19, v163, 16
	v_readfirstlane_b32 s12, v80
	v_lshlrev_b32_e32 v82, 4, v81
	v_lshlrev_b32_e32 v83, 5, v81
	s_lshl_b32 s13, s10, 2
	s_add_u32 s13, s13, s12
	s_lshl_b32 s14, s11, 2
	s_mul_i32 s4, s34, 0x1b000
	s_add_u32 s6, s4, 0x2000
	s_add_u32 s7, s4, 0x3000
.Lgro2_batch:
	s_mov_b32 s20, s13
	s_min_u32 s21, s20, 0x27ff
	s_lshl_b32 s21, s21, 11
	s_add_u32 s22, s86, s21
	s_addc_u32 s23, s87, 0
	global_load_dwordx4 v[168:171], v82, s[22:23]
	global_load_dwordx4 v[172:175], v82, s[22:23] offset:1024
	s_add_u32 s22, s78, s21
	s_addc_u32 s23, s79, 0
	global_load_dwordx4 v[176:179], v82, s[22:23]
	global_load_dwordx4 v[180:183], v82, s[22:23] offset:1024
	s_add_u32 s20, s20, s14
	s_min_u32 s21, s20, 0x27ff
	s_lshl_b32 s21, s21, 11
	s_add_u32 s22, s86, s21
	s_addc_u32 s23, s87, 0
	global_load_dwordx4 v[184:187], v82, s[22:23]
	global_load_dwordx4 v[188:191], v82, s[22:23] offset:1024
	s_add_u32 s22, s78, s21
	s_addc_u32 s23, s79, 0
	global_load_dwordx4 v[192:195], v82, s[22:23]
	global_load_dwordx4 v[196:199], v82, s[22:23] offset:1024
	s_add_u32 s20, s20, s14
	s_min_u32 s21, s20, 0x27ff
	s_lshl_b32 s21, s21, 11
	s_add_u32 s22, s86, s21
	s_addc_u32 s23, s87, 0
	global_load_dwordx4 v[200:203], v82, s[22:23]
	global_load_dwordx4 v[204:207], v82, s[22:23] offset:1024
	s_add_u32 s22, s78, s21
	s_addc_u32 s23, s79, 0
	global_load_dwordx4 v[208:211], v82, s[22:23]
	global_load_dwordx4 v[212:215], v82, s[22:23] offset:1024
	s_add_u32 s20, s20, s14
	s_min_u32 s21, s20, 0x27ff
	s_lshl_b32 s21, s21, 11
	s_add_u32 s22, s86, s21
	s_addc_u32 s23, s87, 0
	global_load_dwordx4 v[216:219], v82, s[22:23]
	global_load_dwordx4 v[220:223], v82, s[22:23] offset:1024
	s_add_u32 s22, s78, s21
	s_addc_u32 s23, s79, 0
	global_load_dwordx4 v[224:227], v82, s[22:23]
	global_load_dwordx4 v[228:231], v82, s[22:23] offset:1024
	s_add_u32 s20, s20, s14
	s_min_u32 s21, s20, 0x27ff
	s_lshl_b32 s21, s21, 11
	s_add_u32 s22, s86, s21
	s_addc_u32 s23, s87, 0
	global_load_dwordx4 v[232:235], v82, s[22:23]
	global_load_dwordx4 v[236:239], v82, s[22:23] offset:1024
	s_add_u32 s22, s78, s21
	s_addc_u32 s23, s79, 0
	global_load_dwordx4 v[240:243], v82, s[22:23]
	global_load_dwordx4 v[244:247], v82, s[22:23] offset:1024
	s_mov_b32 s15, -1
	s_mov_b32 s20, s13
	s_cmp_ge_u32 s20, 0x2800
	s_cbranch_scc1 .Lgro2_bend
	s_sub_u32 s4, s20, 0x2000
	s_lshr_b32 s4, s4, 10
	s_add_u32 s4, s4, 1
	s_cmp_lt_u32 s20, 0x2000
	s_cselect_b32 s4, 0, s4
	s_cmp_eq_u32 s4, s15
	s_cbranch_scc1 .Lgro2_r0_same
	s_mov_b32 s15, s4
	s_mul_i32 s4, s4, 0x9000
	s_add_u32 s32, s4, s6
	s_add_u32 s22, s16, s32
	s_addc_u32 s23, s17, 0
	global_load_dwordx4 v[0:3], v83, s[22:23]
	global_load_dwordx4 v[4:7], v83, s[22:23] offset:16
	global_load_dwordx4 v[8:11], v83, s[22:23] offset:2048
	global_load_dwordx4 v[12:15], v83, s[22:23] offset:2064
	s_add_u32 s32, s4, s7
	s_add_u32 s22, s16, s32
	s_addc_u32 s23, s17, 0
	global_load_dwordx4 v[16:19], v83, s[22:23]
	global_load_dwordx4 v[20:23], v83, s[22:23] offset:16
	global_load_dwordx4 v[24:27], v83, s[22:23] offset:2048
	global_load_dwordx4 v[28:31], v83, s[22:23] offset:2064
	s_add_u32 s22, s22, 0x1000
	s_addc_u32 s23, s23, 0
	global_load_dwordx4 v[32:35], v83, s[22:23]
	global_load_dwordx4 v[36:39], v83, s[22:23] offset:16
	global_load_dwordx4 v[40:43], v83, s[22:23] offset:2048
	global_load_dwordx4 v[44:47], v83, s[22:23] offset:2064
	s_waitcnt vmcnt(0)
	s_branch .Lgro2_r0_go
.Lgro2_r0_same:
	s_waitcnt vmcnt(16)
.Lgro2_r0_go:
	v_lshlrev_b32_e32 v48, 16, v168
	v_and_b32_e32 v49, 0xffff0000, v168
	v_lshlrev_b32_e32 v50, 16, v169
	v_and_b32_e32 v51, 0xffff0000, v169
	v_lshlrev_b32_e32 v52, 16, v170
	v_and_b32_e32 v53, 0xffff0000, v170
	v_lshlrev_b32_e32 v54, 16, v171
	v_and_b32_e32 v55, 0xffff0000, v171
	v_lshlrev_b32_e32 v56, 16, v172
	v_and_b32_e32 v57, 0xffff0000, v172
	v_lshlrev_b32_e32 v58, 16, v173
	v_and_b32_e32 v59, 0xffff0000, v173
	v_lshlrev_b32_e32 v60, 16, v174
	v_and_b32_e32 v61, 0xffff0000, v174
	v_lshlrev_b32_e32 v62, 16, v175
	v_and_b32_e32 v63, 0xffff0000, v175
	v_lshlrev_b32_e32 v64, 16, v176
	v_and_b32_e32 v65, 0xffff0000, v176
	v_lshlrev_b32_e32 v66, 16, v177
	v_and_b32_e32 v67, 0xffff0000, v177
	v_lshlrev_b32_e32 v68, 16, v178
	v_and_b32_e32 v69, 0xffff0000, v178
	v_lshlrev_b32_e32 v70, 16, v179
	v_and_b32_e32 v71, 0xffff0000, v179
	v_lshlrev_b32_e32 v72, 16, v180
	v_and_b32_e32 v73, 0xffff0000, v180
	v_lshlrev_b32_e32 v74, 16, v181
	v_and_b32_e32 v75, 0xffff0000, v181
	v_lshlrev_b32_e32 v76, 16, v182
	v_and_b32_e32 v77, 0xffff0000, v182
	v_lshlrev_b32_e32 v78, 16, v183
	v_and_b32_e32 v79, 0xffff0000, v183
	v_mul_f32_e32 v88, v64, v64
	v_mul_f32_e32 v89, v65, v65
	v_mul_f32_e32 v90, v66, v66
	v_mul_f32_e32 v91, v67, v67
	v_fmac_f32_e32 v88, v68, v68
	v_fmac_f32_e32 v89, v69, v69
	v_fmac_f32_e32 v90, v70, v70
	v_fmac_f32_e32 v91, v71, v71
	v_fmac_f32_e32 v88, v72, v72
	v_fmac_f32_e32 v89, v73, v73
	v_fmac_f32_e32 v90, v74, v74
	v_fmac_f32_e32 v91, v75, v75
	v_fmac_f32_e32 v88, v76, v76
	v_fmac_f32_e32 v89, v77, v77
	v_fmac_f32_e32 v90, v78, v78
	v_fmac_f32_e32 v91, v79, v79
	v_add_f32_e32 v88, v88, v89
	v_add_f32_e32 v90, v90, v91
	v_add_f32_e32 v84, v88, v90
	s_nop 1
	v_add_f32_dpp v84, v84, v84 quad_perm:[1,0,3,2] row_mask:0xf bank_mask:0xf bound_ctrl:1
	s_nop 1
	v_add_f32_dpp v84, v84, v84 quad_perm:[2,3,0,1] row_mask:0xf bank_mask:0xf bound_ctrl:1
	s_nop 1
	v_add_f32_dpp v84, v84, v84 row_half_mirror row_mask:0xf bank_mask:0xf bound_ctrl:1
	s_nop 1
	v_add_f32_dpp v84, v84, v84 row_mirror row_mask:0xf bank_mask:0xf bound_ctrl:1
	s_nop 0
	v_readlane_b32 s44, v84, 0
	v_readlane_b32 s46, v84, 16
	v_readlane_b32 s48, v84, 32
	v_readlane_b32 s50, v84, 48
	s_nop 0
	v_mov_b32_e32 v85, s44
	v_mov_b32_e32 v86, s48
	v_add_f32_e32 v85, s46, v85
	v_add_f32_e32 v86, s50, v86
	v_add_f32_e32 v84, v85, v86
	v_fmamk_f32 v84, v84, 0x3a800000, v130
	v_rsq_f32_e32 v84, v84
	s_nop 0
	v_mul_f32_e32 v92, v84, v64
	v_fmac_f32_e32 v48, v0, v92
	v_mul_f32_e32 v93, v84, v65
	v_fmac_f32_e32 v49, v1, v93
	v_mul_f32_e32 v94, v84, v66
	v_fmac_f32_e32 v50, v2, v94
	v_mul_f32_e32 v95, v84, v67
	v_fmac_f32_e32 v51, v3, v95
	v_mul_f32_e32 v92, v84, v68
	v_fmac_f32_e32 v52, v4, v92
	v_mul_f32_e32 v93, v84, v69
	v_fmac_f32_e32 v53, v5, v93
	v_mul_f32_e32 v94, v84, v70
	v_fmac_f32_e32 v54, v6, v94
	v_mul_f32_e32 v95, v84, v71
	v_fmac_f32_e32 v55, v7, v95
	v_mul_f32_e32 v92, v84, v72
	v_fmac_f32_e32 v56, v8, v92
	v_mul_f32_e32 v93, v84, v73
	v_fmac_f32_e32 v57, v9, v93
	v_mul_f32_e32 v94, v84, v74
	v_fmac_f32_e32 v58, v10, v94
	v_mul_f32_e32 v95, v84, v75
	v_fmac_f32_e32 v59, v11, v95
	v_mul_f32_e32 v92, v84, v76
	v_fmac_f32_e32 v60, v12, v92
	v_mul_f32_e32 v93, v84, v77
	v_fmac_f32_e32 v61, v13, v93
	v_mul_f32_e32 v94, v84, v78
	v_fmac_f32_e32 v62, v14, v94
	v_mul_f32_e32 v95, v84, v79
	v_fmac_f32_e32 v63, v15, v95
	s_lshl_b32 s21, s20, 11
	s_add_u32 s22, s86, s21
	s_addc_u32 s23, s87, 0
	v_cvt_pk_bf16_f32 v100, v48, v49
	v_cvt_pk_bf16_f32 v101, v50, v51
	v_cvt_pk_bf16_f32 v102, v52, v53
	v_cvt_pk_bf16_f32 v103, v54, v55
	v_cvt_pk_bf16_f32 v104, v56, v57
	v_cvt_pk_bf16_f32 v105, v58, v59
	v_cvt_pk_bf16_f32 v106, v60, v61
	v_cvt_pk_bf16_f32 v107, v62, v63
	global_store_dwordx4 v82, v[100:103], s[22:23]
	global_store_dwordx4 v82, v[104:107], s[22:23] offset:1024
	v_mul_f32_e32 v88, v48, v48
	v_mul_f32_e32 v89, v49, v49
	v_mul_f32_e32 v90, v50, v50
	v_mul_f32_e32 v91, v51, v51
	v_fmac_f32_e32 v88, v52, v52
	v_fmac_f32_e32 v89, v53, v53
	v_fmac_f32_e32 v90, v54, v54
	v_fmac_f32_e32 v91, v55, v55
	v_fmac_f32_e32 v88, v56, v56
	v_fmac_f32_e32 v89, v57, v57
	v_fmac_f32_e32 v90, v58, v58
	v_fmac_f32_e32 v91, v59, v59
	v_fmac_f32_e32 v88, v60, v60
	v_fmac_f32_e32 v89, v61, v61
	v_fmac_f32_e32 v90, v62, v62
	v_fmac_f32_e32 v91, v63, v63
	v_add_f32_e32 v88, v88, v89
	v_add_f32_e32 v90, v90, v91
	v_add_f32_e32 v84, v88, v90
	s_nop 1
	v_add_f32_dpp v84, v84, v84 quad_perm:[1,0,3,2] row_mask:0xf bank_mask:0xf bound_ctrl:1
	s_nop 1
	v_add_f32_dpp v84, v84, v84 quad_perm:[2,3,0,1] row_mask:0xf bank_mask:0xf bound_ctrl:1
	s_nop 1
	v_add_f32_dpp v84, v84, v84 row_half_mirror row_mask:0xf bank_mask:0xf bound_ctrl:1
	s_nop 1
	v_add_f32_dpp v84, v84, v84 row_mirror row_mask:0xf bank_mask:0xf bound_ctrl:1
	s_nop 0
	v_readlane_b32 s44, v84, 0
	v_readlane_b32 s46, v84, 16
	v_readlane_b32 s48, v84, 32
	v_readlane_b32 s50, v84, 48
	s_nop 0
	v_mov_b32_e32 v85, s44
	v_mov_b32_e32 v86, s48
	v_add_f32_e32 v85, s46, v85
	v_add_f32_e32 v86, s50, v86
	v_add_f32_e32 v84, v85, v86
	v_fmamk_f32 v84, v84, 0x3a800000, v130
	v_rsq_f32_e32 v84, v84
	s_nop 0
	v_mul_f32_e32 v92, v48, v84
	v_fma_f32 v64, v92, v32, v16
	v_mul_f32_e32 v93, v49, v84
	v_fma_f32 v65, v93, v33, v17
	v_mul_f32_e32 v94, v50, v84
	v_fma_f32 v66, v94, v34, v18
	v_mul_f32_e32 v95, v51, v84
	v_fma_f32 v67, v95, v35, v19
	v_mul_f32_e32 v92, v52, v84
	v_fma_f32 v68, v92, v36, v20
	v_mul_f32_e32 v93, v53, v84
	v_fma_f32 v69, v93, v37, v21
	v_mul_f32_e32 v94, v54, v84
	v_fma_f32 v70, v94, v38, v22
	v_mul_f32_e32 v95, v55, v84
	v_fma_f32 v71, v95, v39, v23
	v_mul_f32_e32 v92, v56, v84
	v_fma_f32 v72, v92, v40, v24
	v_mul_f32_e32 v93, v57, v84
	v_fma_f32 v73, v93, v41, v25
	v_mul_f32_e32 v94, v58, v84
	v_fma_f32 v74, v94, v42, v26
	v_mul_f32_e32 v95, v59, v84
	v_fma_f32 v75, v95, v43, v27
	v_mul_f32_e32 v92, v60, v84
	v_fma_f32 v76, v92, v44, v28
	v_mul_f32_e32 v93, v61, v84
	v_fma_f32 v77, v93, v45, v29
	v_mul_f32_e32 v94, v62, v84
	v_fma_f32 v78, v94, v46, v30
	v_mul_f32_e32 v95, v63, v84
	v_fma_f32 v79, v95, v47, v31
	s_add_u32 s22, s18, s21
	s_addc_u32 s23, s19, 0
	v_cvt_pk_bf16_f32 v108, v64, v65
	v_cvt_pk_bf16_f32 v109, v66, v67
	v_cvt_pk_bf16_f32 v110, v68, v69
	v_cvt_pk_bf16_f32 v111, v70, v71
	v_cvt_pk_bf16_f32 v112, v72, v73
	v_cvt_pk_bf16_f32 v113, v74, v75
	v_cvt_pk_bf16_f32 v114, v76, v77
	v_cvt_pk_bf16_f32 v115, v78, v79
	global_store_dwordx4 v82, v[108:111], s[22:23]
	global_store_dwordx4 v82, v[112:115], s[22:23] offset:1024
	s_add_u32 s20, s20, s14
	s_cmp_ge_u32 s20, 0x2800
	s_cbranch_scc1 .Lgro2_bend
	s_sub_u32 s4, s20, 0x2000
	s_lshr_b32 s4, s4, 10
	s_add_u32 s4, s4, 1
	s_cmp_lt_u32 s20, 0x2000
	s_cselect_b32 s4, 0, s4
	s_cmp_eq_u32 s4, s15
	s_cbranch_scc1 .Lgro2_r1_same
	s_mov_b32 s15, s4
	s_mul_i32 s4, s4, 0x9000
	s_add_u32 s32, s4, s6
	s_add_u32 s22, s16, s32
	s_addc_u32 s23, s17, 0
	global_load_dwordx4 v[0:3], v83, s[22:23]
	global_load_dwordx4 v[4:7], v83, s[22:23] offset:16
	global_load_dwordx4 v[8:11], v83, s[22:23] offset:2048
	global_load_dwordx4 v[12:15], v83, s[22:23] offset:2064
	s_add_u32 s32, s4, s7
	s_add_u32 s22, s16, s32
	s_addc_u32 s23, s17, 0
	global_load_dwordx4 v[16:19], v83, s[22:23]
	global_load_dwordx4 v[20:23], v83, s[22:23] offset:16
	global_load_dwordx4 v[24:27], v83, s[22:23] offset:2048
	global_load_dwordx4 v[28:31], v83, s[22:23] offset:2064
	s_add_u32 s22, s22, 0x1000
	s_addc_u32 s23, s23, 0
	global_load_dwordx4 v[32:35], v83, s[22:23]
	global_load_dwordx4 v[36:39], v83, s[22:23] offset:16
	global_load_dwordx4 v[40:43], v83, s[22:23] offset:2048
	global_load_dwordx4 v[44:47], v83, s[22:23] offset:2064
	s_waitcnt vmcnt(0)
	s_branch .Lgro2_r1_go
.Lgro2_r1_same:
	s_waitcnt vmcnt(12)
.Lgro2_r1_go:
	v_lshlrev_b32_e32 v48, 16, v184
	v_and_b32_e32 v49, 0xffff0000, v184
	v_lshlrev_b32_e32 v50, 16, v185
	v_and_b32_e32 v51, 0xffff0000, v185
	v_lshlrev_b32_e32 v52, 16, v186
	v_and_b32_e32 v53, 0xffff0000, v186
	v_lshlrev_b32_e32 v54, 16, v187
	v_and_b32_e32 v55, 0xffff0000, v187
	v_lshlrev_b32_e32 v56, 16, v188
	v_and_b32_e32 v57, 0xffff0000, v188
	v_lshlrev_b32_e32 v58, 16, v189
	v_and_b32_e32 v59, 0xffff0000, v189
	v_lshlrev_b32_e32 v60, 16, v190
	v_and_b32_e32 v61, 0xffff0000, v190
	v_lshlrev_b32_e32 v62, 16, v191
	v_and_b32_e32 v63, 0xffff0000, v191
	v_lshlrev_b32_e32 v64, 16, v192
	v_and_b32_e32 v65, 0xffff0000, v192
	v_lshlrev_b32_e32 v66, 16, v193
	v_and_b32_e32 v67, 0xffff0000, v193
	v_lshlrev_b32_e32 v68, 16, v194
	v_and_b32_e32 v69, 0xffff0000, v194
	v_lshlrev_b32_e32 v70, 16, v195
	v_and_b32_e32 v71, 0xffff0000, v195
	v_lshlrev_b32_e32 v72, 16, v196
	v_and_b32_e32 v73, 0xffff0000, v196
	v_lshlrev_b32_e32 v74, 16, v197
	v_and_b32_e32 v75, 0xffff0000, v197
	v_lshlrev_b32_e32 v76, 16, v198
	v_and_b32_e32 v77, 0xffff0000, v198
	v_lshlrev_b32_e32 v78, 16, v199
	v_and_b32_e32 v79, 0xffff0000, v199
	v_mul_f32_e32 v88, v64, v64
	v_mul_f32_e32 v89, v65, v65
	v_mul_f32_e32 v90, v66, v66
	v_mul_f32_e32 v91, v67, v67
	v_fmac_f32_e32 v88, v68, v68
	v_fmac_f32_e32 v89, v69, v69
	v_fmac_f32_e32 v90, v70, v70
	v_fmac_f32_e32 v91, v71, v71
	v_fmac_f32_e32 v88, v72, v72
	v_fmac_f32_e32 v89, v73, v73
	v_fmac_f32_e32 v90, v74, v74
	v_fmac_f32_e32 v91, v75, v75
	v_fmac_f32_e32 v88, v76, v76
	v_fmac_f32_e32 v89, v77, v77
	v_fmac_f32_e32 v90, v78, v78
	v_fmac_f32_e32 v91, v79, v79
	v_add_f32_e32 v88, v88, v89
	v_add_f32_e32 v90, v90, v91
	v_add_f32_e32 v84, v88, v90
	s_nop 1
	v_add_f32_dpp v84, v84, v84 quad_perm:[1,0,3,2] row_mask:0xf bank_mask:0xf bound_ctrl:1
	s_nop 1
	v_add_f32_dpp v84, v84, v84 quad_perm:[2,3,0,1] row_mask:0xf bank_mask:0xf bound_ctrl:1
	s_nop 1
	v_add_f32_dpp v84, v84, v84 row_half_mirror row_mask:0xf bank_mask:0xf bound_ctrl:1
	s_nop 1
	v_add_f32_dpp v84, v84, v84 row_mirror row_mask:0xf bank_mask:0xf bound_ctrl:1
	s_nop 0
	v_readlane_b32 s44, v84, 0
	v_readlane_b32 s46, v84, 16
	v_readlane_b32 s48, v84, 32
	v_readlane_b32 s50, v84, 48
	s_nop 0
	v_mov_b32_e32 v85, s44
	v_mov_b32_e32 v86, s48
	v_add_f32_e32 v85, s46, v85
	v_add_f32_e32 v86, s50, v86
	v_add_f32_e32 v84, v85, v86
	v_fmamk_f32 v84, v84, 0x3a800000, v130
	v_rsq_f32_e32 v84, v84
	s_nop 0
	v_mul_f32_e32 v92, v84, v64
	v_fmac_f32_e32 v48, v0, v92
	v_mul_f32_e32 v93, v84, v65
	v_fmac_f32_e32 v49, v1, v93
	v_mul_f32_e32 v94, v84, v66
	v_fmac_f32_e32 v50, v2, v94
	v_mul_f32_e32 v95, v84, v67
	v_fmac_f32_e32 v51, v3, v95
	v_mul_f32_e32 v92, v84, v68
	v_fmac_f32_e32 v52, v4, v92
	v_mul_f32_e32 v93, v84, v69
	v_fmac_f32_e32 v53, v5, v93
	v_mul_f32_e32 v94, v84, v70
	v_fmac_f32_e32 v54, v6, v94
	v_mul_f32_e32 v95, v84, v71
	v_fmac_f32_e32 v55, v7, v95
	v_mul_f32_e32 v92, v84, v72
	v_fmac_f32_e32 v56, v8, v92
	v_mul_f32_e32 v93, v84, v73
	v_fmac_f32_e32 v57, v9, v93
	v_mul_f32_e32 v94, v84, v74
	v_fmac_f32_e32 v58, v10, v94
	v_mul_f32_e32 v95, v84, v75
	v_fmac_f32_e32 v59, v11, v95
	v_mul_f32_e32 v92, v84, v76
	v_fmac_f32_e32 v60, v12, v92
	v_mul_f32_e32 v93, v84, v77
	v_fmac_f32_e32 v61, v13, v93
	v_mul_f32_e32 v94, v84, v78
	v_fmac_f32_e32 v62, v14, v94
	v_mul_f32_e32 v95, v84, v79
	v_fmac_f32_e32 v63, v15, v95
	s_lshl_b32 s21, s20, 11
	s_add_u32 s22, s86, s21
	s_addc_u32 s23, s87, 0
	v_cvt_pk_bf16_f32 v100, v48, v49
	v_cvt_pk_bf16_f32 v101, v50, v51
	v_cvt_pk_bf16_f32 v102, v52, v53
	v_cvt_pk_bf16_f32 v103, v54, v55
	v_cvt_pk_bf16_f32 v104, v56, v57
	v_cvt_pk_bf16_f32 v105, v58, v59
	v_cvt_pk_bf16_f32 v106, v60, v61
	v_cvt_pk_bf16_f32 v107, v62, v63
	global_store_dwordx4 v82, v[100:103], s[22:23]
	global_store_dwordx4 v82, v[104:107], s[22:23] offset:1024
	v_mul_f32_e32 v88, v48, v48
	v_mul_f32_e32 v89, v49, v49
	v_mul_f32_e32 v90, v50, v50
	v_mul_f32_e32 v91, v51, v51
	v_fmac_f32_e32 v88, v52, v52
	v_fmac_f32_e32 v89, v53, v53
	v_fmac_f32_e32 v90, v54, v54
	v_fmac_f32_e32 v91, v55, v55
	v_fmac_f32_e32 v88, v56, v56
	v_fmac_f32_e32 v89, v57, v57
	v_fmac_f32_e32 v90, v58, v58
	v_fmac_f32_e32 v91, v59, v59
	v_fmac_f32_e32 v88, v60, v60
	v_fmac_f32_e32 v89, v61, v61
	v_fmac_f32_e32 v90, v62, v62
	v_fmac_f32_e32 v91, v63, v63
	v_add_f32_e32 v88, v88, v89
	v_add_f32_e32 v90, v90, v91
	v_add_f32_e32 v84, v88, v90
	s_nop 1
	v_add_f32_dpp v84, v84, v84 quad_perm:[1,0,3,2] row_mask:0xf bank_mask:0xf bound_ctrl:1
	s_nop 1
	v_add_f32_dpp v84, v84, v84 quad_perm:[2,3,0,1] row_mask:0xf bank_mask:0xf bound_ctrl:1
	s_nop 1
	v_add_f32_dpp v84, v84, v84 row_half_mirror row_mask:0xf bank_mask:0xf bound_ctrl:1
	s_nop 1
	v_add_f32_dpp v84, v84, v84 row_mirror row_mask:0xf bank_mask:0xf bound_ctrl:1
	s_nop 0
	v_readlane_b32 s44, v84, 0
	v_readlane_b32 s46, v84, 16
	v_readlane_b32 s48, v84, 32
	v_readlane_b32 s50, v84, 48
	s_nop 0
	v_mov_b32_e32 v85, s44
	v_mov_b32_e32 v86, s48
	v_add_f32_e32 v85, s46, v85
	v_add_f32_e32 v86, s50, v86
	v_add_f32_e32 v84, v85, v86
	v_fmamk_f32 v84, v84, 0x3a800000, v130
	v_rsq_f32_e32 v84, v84
	s_nop 0
	v_mul_f32_e32 v92, v48, v84
	v_fma_f32 v64, v92, v32, v16
	v_mul_f32_e32 v93, v49, v84
	v_fma_f32 v65, v93, v33, v17
	v_mul_f32_e32 v94, v50, v84
	v_fma_f32 v66, v94, v34, v18
	v_mul_f32_e32 v95, v51, v84
	v_fma_f32 v67, v95, v35, v19
	v_mul_f32_e32 v92, v52, v84
	v_fma_f32 v68, v92, v36, v20
	v_mul_f32_e32 v93, v53, v84
	v_fma_f32 v69, v93, v37, v21
	v_mul_f32_e32 v94, v54, v84
	v_fma_f32 v70, v94, v38, v22
	v_mul_f32_e32 v95, v55, v84
	v_fma_f32 v71, v95, v39, v23
	v_mul_f32_e32 v92, v56, v84
	v_fma_f32 v72, v92, v40, v24
	v_mul_f32_e32 v93, v57, v84
	v_fma_f32 v73, v93, v41, v25
	v_mul_f32_e32 v94, v58, v84
	v_fma_f32 v74, v94, v42, v26
	v_mul_f32_e32 v95, v59, v84
	v_fma_f32 v75, v95, v43, v27
	v_mul_f32_e32 v92, v60, v84
	v_fma_f32 v76, v92, v44, v28
	v_mul_f32_e32 v93, v61, v84
	v_fma_f32 v77, v93, v45, v29
	v_mul_f32_e32 v94, v62, v84
	v_fma_f32 v78, v94, v46, v30
	v_mul_f32_e32 v95, v63, v84
	v_fma_f32 v79, v95, v47, v31
	s_add_u32 s22, s18, s21
	s_addc_u32 s23, s19, 0
	v_cvt_pk_bf16_f32 v108, v64, v65
	v_cvt_pk_bf16_f32 v109, v66, v67
	v_cvt_pk_bf16_f32 v110, v68, v69
	v_cvt_pk_bf16_f32 v111, v70, v71
	v_cvt_pk_bf16_f32 v112, v72, v73
	v_cvt_pk_bf16_f32 v113, v74, v75
	v_cvt_pk_bf16_f32 v114, v76, v77
	v_cvt_pk_bf16_f32 v115, v78, v79
	global_store_dwordx4 v82, v[108:111], s[22:23]
	global_store_dwordx4 v82, v[112:115], s[22:23] offset:1024
	s_add_u32 s20, s20, s14
	s_cmp_ge_u32 s20, 0x2800
	s_cbranch_scc1 .Lgro2_bend
	s_sub_u32 s4, s20, 0x2000
	s_lshr_b32 s4, s4, 10
	s_add_u32 s4, s4, 1
	s_cmp_lt_u32 s20, 0x2000
	s_cselect_b32 s4, 0, s4
	s_cmp_eq_u32 s4, s15
	s_cbranch_scc1 .Lgro2_r2_same
	s_mov_b32 s15, s4
	s_mul_i32 s4, s4, 0x9000
	s_add_u32 s32, s4, s6
	s_add_u32 s22, s16, s32
	s_addc_u32 s23, s17, 0
	global_load_dwordx4 v[0:3], v83, s[22:23]
	global_load_dwordx4 v[4:7], v83, s[22:23] offset:16
	global_load_dwordx4 v[8:11], v83, s[22:23] offset:2048
	global_load_dwordx4 v[12:15], v83, s[22:23] offset:2064
	s_add_u32 s32, s4, s7
	s_add_u32 s22, s16, s32
	s_addc_u32 s23, s17, 0
	global_load_dwordx4 v[16:19], v83, s[22:23]
	global_load_dwordx4 v[20:23], v83, s[22:23] offset:16
	global_load_dwordx4 v[24:27], v83, s[22:23] offset:2048
	global_load_dwordx4 v[28:31], v83, s[22:23] offset:2064
	s_add_u32 s22, s22, 0x1000
	s_addc_u32 s23, s23, 0
	global_load_dwordx4 v[32:35], v83, s[22:23]
	global_load_dwordx4 v[36:39], v83, s[22:23] offset:16
	global_load_dwordx4 v[40:43], v83, s[22:23] offset:2048
	global_load_dwordx4 v[44:47], v83, s[22:23] offset:2064
	s_waitcnt vmcnt(0)
	s_branch .Lgro2_r2_go
.Lgro2_r2_same:
	s_waitcnt vmcnt(8)
.Lgro2_r2_go:
	v_lshlrev_b32_e32 v48, 16, v200
	v_and_b32_e32 v49, 0xffff0000, v200
	v_lshlrev_b32_e32 v50, 16, v201
	v_and_b32_e32 v51, 0xffff0000, v201
	v_lshlrev_b32_e32 v52, 16, v202
	v_and_b32_e32 v53, 0xffff0000, v202
	v_lshlrev_b32_e32 v54, 16, v203
	v_and_b32_e32 v55, 0xffff0000, v203
	v_lshlrev_b32_e32 v56, 16, v204
	v_and_b32_e32 v57, 0xffff0000, v204
	v_lshlrev_b32_e32 v58, 16, v205
	v_and_b32_e32 v59, 0xffff0000, v205
	v_lshlrev_b32_e32 v60, 16, v206
	v_and_b32_e32 v61, 0xffff0000, v206
	v_lshlrev_b32_e32 v62, 16, v207
	v_and_b32_e32 v63, 0xffff0000, v207
	v_lshlrev_b32_e32 v64, 16, v208
	v_and_b32_e32 v65, 0xffff0000, v208
	v_lshlrev_b32_e32 v66, 16, v209
	v_and_b32_e32 v67, 0xffff0000, v209
	v_lshlrev_b32_e32 v68, 16, v210
	v_and_b32_e32 v69, 0xffff0000, v210
	v_lshlrev_b32_e32 v70, 16, v211
	v_and_b32_e32 v71, 0xffff0000, v211
	v_lshlrev_b32_e32 v72, 16, v212
	v_and_b32_e32 v73, 0xffff0000, v212
	v_lshlrev_b32_e32 v74, 16, v213
	v_and_b32_e32 v75, 0xffff0000, v213
	v_lshlrev_b32_e32 v76, 16, v214
	v_and_b32_e32 v77, 0xffff0000, v214
	v_lshlrev_b32_e32 v78, 16, v215
	v_and_b32_e32 v79, 0xffff0000, v215
	v_mul_f32_e32 v88, v64, v64
	v_mul_f32_e32 v89, v65, v65
	v_mul_f32_e32 v90, v66, v66
	v_mul_f32_e32 v91, v67, v67
	v_fmac_f32_e32 v88, v68, v68
	v_fmac_f32_e32 v89, v69, v69
	v_fmac_f32_e32 v90, v70, v70
	v_fmac_f32_e32 v91, v71, v71
	v_fmac_f32_e32 v88, v72, v72
	v_fmac_f32_e32 v89, v73, v73
	v_fmac_f32_e32 v90, v74, v74
	v_fmac_f32_e32 v91, v75, v75
	v_fmac_f32_e32 v88, v76, v76
	v_fmac_f32_e32 v89, v77, v77
	v_fmac_f32_e32 v90, v78, v78
	v_fmac_f32_e32 v91, v79, v79
	v_add_f32_e32 v88, v88, v89
	v_add_f32_e32 v90, v90, v91
	v_add_f32_e32 v84, v88, v90
	s_nop 1
	v_add_f32_dpp v84, v84, v84 quad_perm:[1,0,3,2] row_mask:0xf bank_mask:0xf bound_ctrl:1
	s_nop 1
	v_add_f32_dpp v84, v84, v84 quad_perm:[2,3,0,1] row_mask:0xf bank_mask:0xf bound_ctrl:1
	s_nop 1
	v_add_f32_dpp v84, v84, v84 row_half_mirror row_mask:0xf bank_mask:0xf bound_ctrl:1
	s_nop 1
	v_add_f32_dpp v84, v84, v84 row_mirror row_mask:0xf bank_mask:0xf bound_ctrl:1
	s_nop 0
	v_readlane_b32 s44, v84, 0
	v_readlane_b32 s46, v84, 16
	v_readlane_b32 s48, v84, 32
	v_readlane_b32 s50, v84, 48
	s_nop 0
	v_mov_b32_e32 v85, s44
	v_mov_b32_e32 v86, s48
	v_add_f32_e32 v85, s46, v85
	v_add_f32_e32 v86, s50, v86
	v_add_f32_e32 v84, v85, v86
	v_fmamk_f32 v84, v84, 0x3a800000, v130
	v_rsq_f32_e32 v84, v84
	s_nop 0
	v_mul_f32_e32 v92, v84, v64
	v_fmac_f32_e32 v48, v0, v92
	v_mul_f32_e32 v93, v84, v65
	v_fmac_f32_e32 v49, v1, v93
	v_mul_f32_e32 v94, v84, v66
	v_fmac_f32_e32 v50, v2, v94
	v_mul_f32_e32 v95, v84, v67
	v_fmac_f32_e32 v51, v3, v95
	v_mul_f32_e32 v92, v84, v68
	v_fmac_f32_e32 v52, v4, v92
	v_mul_f32_e32 v93, v84, v69
	v_fmac_f32_e32 v53, v5, v93
	v_mul_f32_e32 v94, v84, v70
	v_fmac_f32_e32 v54, v6, v94
	v_mul_f32_e32 v95, v84, v71
	v_fmac_f32_e32 v55, v7, v95
	v_mul_f32_e32 v92, v84, v72
	v_fmac_f32_e32 v56, v8, v92
	v_mul_f32_e32 v93, v84, v73
	v_fmac_f32_e32 v57, v9, v93
	v_mul_f32_e32 v94, v84, v74
	v_fmac_f32_e32 v58, v10, v94
	v_mul_f32_e32 v95, v84, v75
	v_fmac_f32_e32 v59, v11, v95
	v_mul_f32_e32 v92, v84, v76
	v_fmac_f32_e32 v60, v12, v92
	v_mul_f32_e32 v93, v84, v77
	v_fmac_f32_e32 v61, v13, v93
	v_mul_f32_e32 v94, v84, v78
	v_fmac_f32_e32 v62, v14, v94
	v_mul_f32_e32 v95, v84, v79
	v_fmac_f32_e32 v63, v15, v95
	s_lshl_b32 s21, s20, 11
	s_add_u32 s22, s86, s21
	s_addc_u32 s23, s87, 0
	v_cvt_pk_bf16_f32 v100, v48, v49
	v_cvt_pk_bf16_f32 v101, v50, v51
	v_cvt_pk_bf16_f32 v102, v52, v53
	v_cvt_pk_bf16_f32 v103, v54, v55
	v_cvt_pk_bf16_f32 v104, v56, v57
	v_cvt_pk_bf16_f32 v105, v58, v59
	v_cvt_pk_bf16_f32 v106, v60, v61
	v_cvt_pk_bf16_f32 v107, v62, v63
	global_store_dwordx4 v82, v[100:103], s[22:23]
	global_store_dwordx4 v82, v[104:107], s[22:23] offset:1024
	v_mul_f32_e32 v88, v48, v48
	v_mul_f32_e32 v89, v49, v49
	v_mul_f32_e32 v90, v50, v50
	v_mul_f32_e32 v91, v51, v51
	v_fmac_f32_e32 v88, v52, v52
	v_fmac_f32_e32 v89, v53, v53
	v_fmac_f32_e32 v90, v54, v54
	v_fmac_f32_e32 v91, v55, v55
	v_fmac_f32_e32 v88, v56, v56
	v_fmac_f32_e32 v89, v57, v57
	v_fmac_f32_e32 v90, v58, v58
	v_fmac_f32_e32 v91, v59, v59
	v_fmac_f32_e32 v88, v60, v60
	v_fmac_f32_e32 v89, v61, v61
	v_fmac_f32_e32 v90, v62, v62
	v_fmac_f32_e32 v91, v63, v63
	v_add_f32_e32 v88, v88, v89
	v_add_f32_e32 v90, v90, v91
	v_add_f32_e32 v84, v88, v90
	s_nop 1
	v_add_f32_dpp v84, v84, v84 quad_perm:[1,0,3,2] row_mask:0xf bank_mask:0xf bound_ctrl:1
	s_nop 1
	v_add_f32_dpp v84, v84, v84 quad_perm:[2,3,0,1] row_mask:0xf bank_mask:0xf bound_ctrl:1
	s_nop 1
	v_add_f32_dpp v84, v84, v84 row_half_mirror row_mask:0xf bank_mask:0xf bound_ctrl:1
	s_nop 1
	v_add_f32_dpp v84, v84, v84 row_mirror row_mask:0xf bank_mask:0xf bound_ctrl:1
	s_nop 0
	v_readlane_b32 s44, v84, 0
	v_readlane_b32 s46, v84, 16
	v_readlane_b32 s48, v84, 32
	v_readlane_b32 s50, v84, 48
	s_nop 0
	v_mov_b32_e32 v85, s44
	v_mov_b32_e32 v86, s48
	v_add_f32_e32 v85, s46, v85
	v_add_f32_e32 v86, s50, v86
	v_add_f32_e32 v84, v85, v86
	v_fmamk_f32 v84, v84, 0x3a800000, v130
	v_rsq_f32_e32 v84, v84
	s_nop 0
	v_mul_f32_e32 v92, v48, v84
	v_fma_f32 v64, v92, v32, v16
	v_mul_f32_e32 v93, v49, v84
	v_fma_f32 v65, v93, v33, v17
	v_mul_f32_e32 v94, v50, v84
	v_fma_f32 v66, v94, v34, v18
	v_mul_f32_e32 v95, v51, v84
	v_fma_f32 v67, v95, v35, v19
	v_mul_f32_e32 v92, v52, v84
	v_fma_f32 v68, v92, v36, v20
	v_mul_f32_e32 v93, v53, v84
	v_fma_f32 v69, v93, v37, v21
	v_mul_f32_e32 v94, v54, v84
	v_fma_f32 v70, v94, v38, v22
	v_mul_f32_e32 v95, v55, v84
	v_fma_f32 v71, v95, v39, v23
	v_mul_f32_e32 v92, v56, v84
	v_fma_f32 v72, v92, v40, v24
	v_mul_f32_e32 v93, v57, v84
	v_fma_f32 v73, v93, v41, v25
	v_mul_f32_e32 v94, v58, v84
	v_fma_f32 v74, v94, v42, v26
	v_mul_f32_e32 v95, v59, v84
	v_fma_f32 v75, v95, v43, v27
	v_mul_f32_e32 v92, v60, v84
	v_fma_f32 v76, v92, v44, v28
	v_mul_f32_e32 v93, v61, v84
	v_fma_f32 v77, v93, v45, v29
	v_mul_f32_e32 v94, v62, v84
	v_fma_f32 v78, v94, v46, v30
	v_mul_f32_e32 v95, v63, v84
	v_fma_f32 v79, v95, v47, v31
	s_add_u32 s22, s18, s21
	s_addc_u32 s23, s19, 0
	v_cvt_pk_bf16_f32 v108, v64, v65
	v_cvt_pk_bf16_f32 v109, v66, v67
	v_cvt_pk_bf16_f32 v110, v68, v69
	v_cvt_pk_bf16_f32 v111, v70, v71
	v_cvt_pk_bf16_f32 v112, v72, v73
	v_cvt_pk_bf16_f32 v113, v74, v75
	v_cvt_pk_bf16_f32 v114, v76, v77
	v_cvt_pk_bf16_f32 v115, v78, v79
	global_store_dwordx4 v82, v[108:111], s[22:23]
	global_store_dwordx4 v82, v[112:115], s[22:23] offset:1024
	s_add_u32 s20, s20, s14
	s_cmp_ge_u32 s20, 0x2800
	s_cbranch_scc1 .Lgro2_bend
	s_sub_u32 s4, s20, 0x2000
	s_lshr_b32 s4, s4, 10
	s_add_u32 s4, s4, 1
	s_cmp_lt_u32 s20, 0x2000
	s_cselect_b32 s4, 0, s4
	s_cmp_eq_u32 s4, s15
	s_cbranch_scc1 .Lgro2_r3_same
	s_mov_b32 s15, s4
	s_mul_i32 s4, s4, 0x9000
	s_add_u32 s32, s4, s6
	s_add_u32 s22, s16, s32
	s_addc_u32 s23, s17, 0
	global_load_dwordx4 v[0:3], v83, s[22:23]
	global_load_dwordx4 v[4:7], v83, s[22:23] offset:16
	global_load_dwordx4 v[8:11], v83, s[22:23] offset:2048
	global_load_dwordx4 v[12:15], v83, s[22:23] offset:2064
	s_add_u32 s32, s4, s7
	s_add_u32 s22, s16, s32
	s_addc_u32 s23, s17, 0
	global_load_dwordx4 v[16:19], v83, s[22:23]
	global_load_dwordx4 v[20:23], v83, s[22:23] offset:16
	global_load_dwordx4 v[24:27], v83, s[22:23] offset:2048
	global_load_dwordx4 v[28:31], v83, s[22:23] offset:2064
	s_add_u32 s22, s22, 0x1000
	s_addc_u32 s23, s23, 0
	global_load_dwordx4 v[32:35], v83, s[22:23]
	global_load_dwordx4 v[36:39], v83, s[22:23] offset:16
	global_load_dwordx4 v[40:43], v83, s[22:23] offset:2048
	global_load_dwordx4 v[44:47], v83, s[22:23] offset:2064
	s_waitcnt vmcnt(0)
	s_branch .Lgro2_r3_go
.Lgro2_r3_same:
	s_waitcnt vmcnt(4)
.Lgro2_r3_go:
	v_lshlrev_b32_e32 v48, 16, v216
	v_and_b32_e32 v49, 0xffff0000, v216
	v_lshlrev_b32_e32 v50, 16, v217
	v_and_b32_e32 v51, 0xffff0000, v217
	v_lshlrev_b32_e32 v52, 16, v218
	v_and_b32_e32 v53, 0xffff0000, v218
	v_lshlrev_b32_e32 v54, 16, v219
	v_and_b32_e32 v55, 0xffff0000, v219
	v_lshlrev_b32_e32 v56, 16, v220
	v_and_b32_e32 v57, 0xffff0000, v220
	v_lshlrev_b32_e32 v58, 16, v221
	v_and_b32_e32 v59, 0xffff0000, v221
	v_lshlrev_b32_e32 v60, 16, v222
	v_and_b32_e32 v61, 0xffff0000, v222
	v_lshlrev_b32_e32 v62, 16, v223
	v_and_b32_e32 v63, 0xffff0000, v223
	v_lshlrev_b32_e32 v64, 16, v224
	v_and_b32_e32 v65, 0xffff0000, v224
	v_lshlrev_b32_e32 v66, 16, v225
	v_and_b32_e32 v67, 0xffff0000, v225
	v_lshlrev_b32_e32 v68, 16, v226
	v_and_b32_e32 v69, 0xffff0000, v226
	v_lshlrev_b32_e32 v70, 16, v227
	v_and_b32_e32 v71, 0xffff0000, v227
	v_lshlrev_b32_e32 v72, 16, v228
	v_and_b32_e32 v73, 0xffff0000, v228
	v_lshlrev_b32_e32 v74, 16, v229
	v_and_b32_e32 v75, 0xffff0000, v229
	v_lshlrev_b32_e32 v76, 16, v230
	v_and_b32_e32 v77, 0xffff0000, v230
	v_lshlrev_b32_e32 v78, 16, v231
	v_and_b32_e32 v79, 0xffff0000, v231
	v_mul_f32_e32 v88, v64, v64
	v_mul_f32_e32 v89, v65, v65
	v_mul_f32_e32 v90, v66, v66
	v_mul_f32_e32 v91, v67, v67
	v_fmac_f32_e32 v88, v68, v68
	v_fmac_f32_e32 v89, v69, v69
	v_fmac_f32_e32 v90, v70, v70
	v_fmac_f32_e32 v91, v71, v71
	v_fmac_f32_e32 v88, v72, v72
	v_fmac_f32_e32 v89, v73, v73
	v_fmac_f32_e32 v90, v74, v74
	v_fmac_f32_e32 v91, v75, v75
	v_fmac_f32_e32 v88, v76, v76
	v_fmac_f32_e32 v89, v77, v77
	v_fmac_f32_e32 v90, v78, v78
	v_fmac_f32_e32 v91, v79, v79
	v_add_f32_e32 v88, v88, v89
	v_add_f32_e32 v90, v90, v91
	v_add_f32_e32 v84, v88, v90
	s_nop 1
	v_add_f32_dpp v84, v84, v84 quad_perm:[1,0,3,2] row_mask:0xf bank_mask:0xf bound_ctrl:1
	s_nop 1
	v_add_f32_dpp v84, v84, v84 quad_perm:[2,3,0,1] row_mask:0xf bank_mask:0xf bound_ctrl:1
	s_nop 1
	v_add_f32_dpp v84, v84, v84 row_half_mirror row_mask:0xf bank_mask:0xf bound_ctrl:1
	s_nop 1
	v_add_f32_dpp v84, v84, v84 row_mirror row_mask:0xf bank_mask:0xf bound_ctrl:1
	s_nop 0
	v_readlane_b32 s44, v84, 0
	v_readlane_b32 s46, v84, 16
	v_readlane_b32 s48, v84, 32
	v_readlane_b32 s50, v84, 48
	s_nop 0
	v_mov_b32_e32 v85, s44
	v_mov_b32_e32 v86, s48
	v_add_f32_e32 v85, s46, v85
	v_add_f32_e32 v86, s50, v86
	v_add_f32_e32 v84, v85, v86
	v_fmamk_f32 v84, v84, 0x3a800000, v130
	v_rsq_f32_e32 v84, v84
	s_nop 0
	v_mul_f32_e32 v92, v84, v64
	v_fmac_f32_e32 v48, v0, v92
	v_mul_f32_e32 v93, v84, v65
	v_fmac_f32_e32 v49, v1, v93
	v_mul_f32_e32 v94, v84, v66
	v_fmac_f32_e32 v50, v2, v94
	v_mul_f32_e32 v95, v84, v67
	v_fmac_f32_e32 v51, v3, v95
	v_mul_f32_e32 v92, v84, v68
	v_fmac_f32_e32 v52, v4, v92
	v_mul_f32_e32 v93, v84, v69
	v_fmac_f32_e32 v53, v5, v93
	v_mul_f32_e32 v94, v84, v70
	v_fmac_f32_e32 v54, v6, v94
	v_mul_f32_e32 v95, v84, v71
	v_fmac_f32_e32 v55, v7, v95
	v_mul_f32_e32 v92, v84, v72
	v_fmac_f32_e32 v56, v8, v92
	v_mul_f32_e32 v93, v84, v73
	v_fmac_f32_e32 v57, v9, v93
	v_mul_f32_e32 v94, v84, v74
	v_fmac_f32_e32 v58, v10, v94
	v_mul_f32_e32 v95, v84, v75
	v_fmac_f32_e32 v59, v11, v95
	v_mul_f32_e32 v92, v84, v76
	v_fmac_f32_e32 v60, v12, v92
	v_mul_f32_e32 v93, v84, v77
	v_fmac_f32_e32 v61, v13, v93
	v_mul_f32_e32 v94, v84, v78
	v_fmac_f32_e32 v62, v14, v94
	v_mul_f32_e32 v95, v84, v79
	v_fmac_f32_e32 v63, v15, v95
	s_lshl_b32 s21, s20, 11
	s_add_u32 s22, s86, s21
	s_addc_u32 s23, s87, 0
	v_cvt_pk_bf16_f32 v100, v48, v49
	v_cvt_pk_bf16_f32 v101, v50, v51
	v_cvt_pk_bf16_f32 v102, v52, v53
	v_cvt_pk_bf16_f32 v103, v54, v55
	v_cvt_pk_bf16_f32 v104, v56, v57
	v_cvt_pk_bf16_f32 v105, v58, v59
	v_cvt_pk_bf16_f32 v106, v60, v61
	v_cvt_pk_bf16_f32 v107, v62, v63
	global_store_dwordx4 v82, v[100:103], s[22:23]
	global_store_dwordx4 v82, v[104:107], s[22:23] offset:1024
	v_mul_f32_e32 v88, v48, v48
	v_mul_f32_e32 v89, v49, v49
	v_mul_f32_e32 v90, v50, v50
	v_mul_f32_e32 v91, v51, v51
	v_fmac_f32_e32 v88, v52, v52
	v_fmac_f32_e32 v89, v53, v53
	v_fmac_f32_e32 v90, v54, v54
	v_fmac_f32_e32 v91, v55, v55
	v_fmac_f32_e32 v88, v56, v56
	v_fmac_f32_e32 v89, v57, v57
	v_fmac_f32_e32 v90, v58, v58
	v_fmac_f32_e32 v91, v59, v59
	v_fmac_f32_e32 v88, v60, v60
	v_fmac_f32_e32 v89, v61, v61
	v_fmac_f32_e32 v90, v62, v62
	v_fmac_f32_e32 v91, v63, v63
	v_add_f32_e32 v88, v88, v89
	v_add_f32_e32 v90, v90, v91
	v_add_f32_e32 v84, v88, v90
	s_nop 1
	v_add_f32_dpp v84, v84, v84 quad_perm:[1,0,3,2] row_mask:0xf bank_mask:0xf bound_ctrl:1
	s_nop 1
	v_add_f32_dpp v84, v84, v84 quad_perm:[2,3,0,1] row_mask:0xf bank_mask:0xf bound_ctrl:1
	s_nop 1
	v_add_f32_dpp v84, v84, v84 row_half_mirror row_mask:0xf bank_mask:0xf bound_ctrl:1
	s_nop 1
	v_add_f32_dpp v84, v84, v84 row_mirror row_mask:0xf bank_mask:0xf bound_ctrl:1
	s_nop 0
	v_readlane_b32 s44, v84, 0
	v_readlane_b32 s46, v84, 16
	v_readlane_b32 s48, v84, 32
	v_readlane_b32 s50, v84, 48
	s_nop 0
	v_mov_b32_e32 v85, s44
	v_mov_b32_e32 v86, s48
	v_add_f32_e32 v85, s46, v85
	v_add_f32_e32 v86, s50, v86
	v_add_f32_e32 v84, v85, v86
	v_fmamk_f32 v84, v84, 0x3a800000, v130
	v_rsq_f32_e32 v84, v84
	s_nop 0
	v_mul_f32_e32 v92, v48, v84
	v_fma_f32 v64, v92, v32, v16
	v_mul_f32_e32 v93, v49, v84
	v_fma_f32 v65, v93, v33, v17
	v_mul_f32_e32 v94, v50, v84
	v_fma_f32 v66, v94, v34, v18
	v_mul_f32_e32 v95, v51, v84
	v_fma_f32 v67, v95, v35, v19
	v_mul_f32_e32 v92, v52, v84
	v_fma_f32 v68, v92, v36, v20
	v_mul_f32_e32 v93, v53, v84
	v_fma_f32 v69, v93, v37, v21
	v_mul_f32_e32 v94, v54, v84
	v_fma_f32 v70, v94, v38, v22
	v_mul_f32_e32 v95, v55, v84
	v_fma_f32 v71, v95, v39, v23
	v_mul_f32_e32 v92, v56, v84
	v_fma_f32 v72, v92, v40, v24
	v_mul_f32_e32 v93, v57, v84
	v_fma_f32 v73, v93, v41, v25
	v_mul_f32_e32 v94, v58, v84
	v_fma_f32 v74, v94, v42, v26
	v_mul_f32_e32 v95, v59, v84
	v_fma_f32 v75, v95, v43, v27
	v_mul_f32_e32 v92, v60, v84
	v_fma_f32 v76, v92, v44, v28
	v_mul_f32_e32 v93, v61, v84
	v_fma_f32 v77, v93, v45, v29
	v_mul_f32_e32 v94, v62, v84
	v_fma_f32 v78, v94, v46, v30
	v_mul_f32_e32 v95, v63, v84
	v_fma_f32 v79, v95, v47, v31
	s_add_u32 s22, s18, s21
	s_addc_u32 s23, s19, 0
	v_cvt_pk_bf16_f32 v108, v64, v65
	v_cvt_pk_bf16_f32 v109, v66, v67
	v_cvt_pk_bf16_f32 v110, v68, v69
	v_cvt_pk_bf16_f32 v111, v70, v71
	v_cvt_pk_bf16_f32 v112, v72, v73
	v_cvt_pk_bf16_f32 v113, v74, v75
	v_cvt_pk_bf16_f32 v114, v76, v77
	v_cvt_pk_bf16_f32 v115, v78, v79
	global_store_dwordx4 v82, v[108:111], s[22:23]
	global_store_dwordx4 v82, v[112:115], s[22:23] offset:1024
	s_add_u32 s20, s20, s14
	s_cmp_ge_u32 s20, 0x2800
	s_cbranch_scc1 .Lgro2_bend
	s_sub_u32 s4, s20, 0x2000
	s_lshr_b32 s4, s4, 10
	s_add_u32 s4, s4, 1
	s_cmp_lt_u32 s20, 0x2000
	s_cselect_b32 s4, 0, s4
	s_cmp_eq_u32 s4, s15
	s_cbranch_scc1 .Lgro2_r4_same
	s_mov_b32 s15, s4
	s_mul_i32 s4, s4, 0x9000
	s_add_u32 s32, s4, s6
	s_add_u32 s22, s16, s32
	s_addc_u32 s23, s17, 0
	global_load_dwordx4 v[0:3], v83, s[22:23]
	global_load_dwordx4 v[4:7], v83, s[22:23] offset:16
	global_load_dwordx4 v[8:11], v83, s[22:23] offset:2048
	global_load_dwordx4 v[12:15], v83, s[22:23] offset:2064
	s_add_u32 s32, s4, s7
	s_add_u32 s22, s16, s32
	s_addc_u32 s23, s17, 0
	global_load_dwordx4 v[16:19], v83, s[22:23]
	global_load_dwordx4 v[20:23], v83, s[22:23] offset:16
	global_load_dwordx4 v[24:27], v83, s[22:23] offset:2048
	global_load_dwordx4 v[28:31], v83, s[22:23] offset:2064
	s_add_u32 s22, s22, 0x1000
	s_addc_u32 s23, s23, 0
	global_load_dwordx4 v[32:35], v83, s[22:23]
	global_load_dwordx4 v[36:39], v83, s[22:23] offset:16
	global_load_dwordx4 v[40:43], v83, s[22:23] offset:2048
	global_load_dwordx4 v[44:47], v83, s[22:23] offset:2064
	s_waitcnt vmcnt(0)
	s_branch .Lgro2_r4_go

.Lgro2_r4_go:
	v_lshlrev_b32_e32 v48, 16, v232
	v_and_b32_e32 v49, 0xffff0000, v232
	v_lshlrev_b32_e32 v50, 16, v233
	v_and_b32_e32 v51, 0xffff0000, v233
	v_lshlrev_b32_e32 v52, 16, v234
	v_and_b32_e32 v53, 0xffff0000, v234
	v_lshlrev_b32_e32 v54, 16, v235
	v_and_b32_e32 v55, 0xffff0000, v235
	v_lshlrev_b32_e32 v56, 16, v236
	v_and_b32_e32 v57, 0xffff0000, v236
	v_lshlrev_b32_e32 v58, 16, v237
	v_and_b32_e32 v59, 0xffff0000, v237
	v_lshlrev_b32_e32 v60, 16, v238
	v_and_b32_e32 v61, 0xffff0000, v238
	v_lshlrev_b32_e32 v62, 16, v239
	v_and_b32_e32 v63, 0xffff0000, v239
	v_lshlrev_b32_e32 v64, 16, v240
	v_and_b32_e32 v65, 0xffff0000, v240
	v_lshlrev_b32_e32 v66, 16, v241
	v_and_b32_e32 v67, 0xffff0000, v241
	v_lshlrev_b32_e32 v68, 16, v242
	v_and_b32_e32 v69, 0xffff0000, v242
	v_lshlrev_b32_e32 v70, 16, v243
	v_and_b32_e32 v71, 0xffff0000, v243
	v_lshlrev_b32_e32 v72, 16, v244
	v_and_b32_e32 v73, 0xffff0000, v244
	v_lshlrev_b32_e32 v74, 16, v245
	v_and_b32_e32 v75, 0xffff0000, v245
	v_lshlrev_b32_e32 v76, 16, v246
	v_and_b32_e32 v77, 0xffff0000, v246
	v_lshlrev_b32_e32 v78, 16, v247
	v_and_b32_e32 v79, 0xffff0000, v247
	v_mul_f32_e32 v88, v64, v64
	v_mul_f32_e32 v89, v65, v65
	v_mul_f32_e32 v90, v66, v66
	v_mul_f32_e32 v91, v67, v67
	v_fmac_f32_e32 v88, v68, v68
	v_fmac_f32_e32 v89, v69, v69
	v_fmac_f32_e32 v90, v70, v70
	v_fmac_f32_e32 v91, v71, v71
	v_fmac_f32_e32 v88, v72, v72
	v_fmac_f32_e32 v89, v73, v73
	v_fmac_f32_e32 v90, v74, v74
	v_fmac_f32_e32 v91, v75, v75
	v_fmac_f32_e32 v88, v76, v76
	v_fmac_f32_e32 v89, v77, v77
	v_fmac_f32_e32 v90, v78, v78
	v_fmac_f32_e32 v91, v79, v79
	v_add_f32_e32 v88, v88, v89
	v_add_f32_e32 v90, v90, v91
	v_add_f32_e32 v84, v88, v90
	s_nop 1
	v_add_f32_dpp v84, v84, v84 quad_perm:[1,0,3,2] row_mask:0xf bank_mask:0xf bound_ctrl:1
	s_nop 1
	v_add_f32_dpp v84, v84, v84 quad_perm:[2,3,0,1] row_mask:0xf bank_mask:0xf bound_ctrl:1
	s_nop 1
	v_add_f32_dpp v84, v84, v84 row_half_mirror row_mask:0xf bank_mask:0xf bound_ctrl:1
	s_nop 1
	v_add_f32_dpp v84, v84, v84 row_mirror row_mask:0xf bank_mask:0xf bound_ctrl:1
	s_nop 0
	v_readlane_b32 s44, v84, 0
	v_readlane_b32 s46, v84, 16
	v_readlane_b32 s48, v84, 32
	v_readlane_b32 s50, v84, 48
	s_nop 0
	v_mov_b32_e32 v85, s44
	v_mov_b32_e32 v86, s48
	v_add_f32_e32 v85, s46, v85
	v_add_f32_e32 v86, s50, v86
	v_add_f32_e32 v84, v85, v86
	v_fmamk_f32 v84, v84, 0x3a800000, v130
	v_rsq_f32_e32 v84, v84
	s_nop 0
	v_mul_f32_e32 v92, v84, v64
	v_fmac_f32_e32 v48, v0, v92
	v_mul_f32_e32 v93, v84, v65
	v_fmac_f32_e32 v49, v1, v93
	v_mul_f32_e32 v94, v84, v66
	v_fmac_f32_e32 v50, v2, v94
	v_mul_f32_e32 v95, v84, v67
	v_fmac_f32_e32 v51, v3, v95
	v_mul_f32_e32 v92, v84, v68
	v_fmac_f32_e32 v52, v4, v92
	v_mul_f32_e32 v93, v84, v69
	v_fmac_f32_e32 v53, v5, v93
	v_mul_f32_e32 v94, v84, v70
	v_fmac_f32_e32 v54, v6, v94
	v_mul_f32_e32 v95, v84, v71
	v_fmac_f32_e32 v55, v7, v95
	v_mul_f32_e32 v92, v84, v72
	v_fmac_f32_e32 v56, v8, v92
	v_mul_f32_e32 v93, v84, v73
	v_fmac_f32_e32 v57, v9, v93
	v_mul_f32_e32 v94, v84, v74
	v_fmac_f32_e32 v58, v10, v94
	v_mul_f32_e32 v95, v84, v75
	v_fmac_f32_e32 v59, v11, v95
	v_mul_f32_e32 v92, v84, v76
	v_fmac_f32_e32 v60, v12, v92
	v_mul_f32_e32 v93, v84, v77
	v_fmac_f32_e32 v61, v13, v93
	v_mul_f32_e32 v94, v84, v78
	v_fmac_f32_e32 v62, v14, v94
	v_mul_f32_e32 v95, v84, v79
	v_fmac_f32_e32 v63, v15, v95
	s_lshl_b32 s21, s20, 11
	s_add_u32 s22, s86, s21
	s_addc_u32 s23, s87, 0
	v_cvt_pk_bf16_f32 v100, v48, v49
	v_cvt_pk_bf16_f32 v101, v50, v51
	v_cvt_pk_bf16_f32 v102, v52, v53
	v_cvt_pk_bf16_f32 v103, v54, v55
	v_cvt_pk_bf16_f32 v104, v56, v57
	v_cvt_pk_bf16_f32 v105, v58, v59
	v_cvt_pk_bf16_f32 v106, v60, v61
	v_cvt_pk_bf16_f32 v107, v62, v63
	global_store_dwordx4 v82, v[100:103], s[22:23]
	global_store_dwordx4 v82, v[104:107], s[22:23] offset:1024
	v_mul_f32_e32 v88, v48, v48
	v_mul_f32_e32 v89, v49, v49
	v_mul_f32_e32 v90, v50, v50
	v_mul_f32_e32 v91, v51, v51
	v_fmac_f32_e32 v88, v52, v52
	v_fmac_f32_e32 v89, v53, v53
	v_fmac_f32_e32 v90, v54, v54
	v_fmac_f32_e32 v91, v55, v55
	v_fmac_f32_e32 v88, v56, v56
	v_fmac_f32_e32 v89, v57, v57
	v_fmac_f32_e32 v90, v58, v58
	v_fmac_f32_e32 v91, v59, v59
	v_fmac_f32_e32 v88, v60, v60
	v_fmac_f32_e32 v89, v61, v61
	v_fmac_f32_e32 v90, v62, v62
	v_fmac_f32_e32 v91, v63, v63
	v_add_f32_e32 v88, v88, v89
	v_add_f32_e32 v90, v90, v91
	v_add_f32_e32 v84, v88, v90
	s_nop 1
	v_add_f32_dpp v84, v84, v84 quad_perm:[1,0,3,2] row_mask:0xf bank_mask:0xf bound_ctrl:1
	s_nop 1
	v_add_f32_dpp v84, v84, v84 quad_perm:[2,3,0,1] row_mask:0xf bank_mask:0xf bound_ctrl:1
	s_nop 1
	v_add_f32_dpp v84, v84, v84 row_half_mirror row_mask:0xf bank_mask:0xf bound_ctrl:1
	s_nop 1
	v_add_f32_dpp v84, v84, v84 row_mirror row_mask:0xf bank_mask:0xf bound_ctrl:1
	s_nop 0
	v_readlane_b32 s44, v84, 0
	v_readlane_b32 s46, v84, 16
	v_readlane_b32 s48, v84, 32
	v_readlane_b32 s50, v84, 48
	s_nop 0
	v_mov_b32_e32 v85, s44
	v_mov_b32_e32 v86, s48
	v_add_f32_e32 v85, s46, v85
	v_add_f32_e32 v86, s50, v86
	v_add_f32_e32 v84, v85, v86
	v_fmamk_f32 v84, v84, 0x3a800000, v130
	v_rsq_f32_e32 v84, v84
	s_nop 0
	v_mul_f32_e32 v92, v48, v84
	v_fma_f32 v64, v92, v32, v16
	v_mul_f32_e32 v93, v49, v84
	v_fma_f32 v65, v93, v33, v17
	v_mul_f32_e32 v94, v50, v84
	v_fma_f32 v66, v94, v34, v18
	v_mul_f32_e32 v95, v51, v84
	v_fma_f32 v67, v95, v35, v19
	v_mul_f32_e32 v92, v52, v84
	v_fma_f32 v68, v92, v36, v20
	v_mul_f32_e32 v93, v53, v84
	v_fma_f32 v69, v93, v37, v21
	v_mul_f32_e32 v94, v54, v84
	v_fma_f32 v70, v94, v38, v22
	v_mul_f32_e32 v95, v55, v84
	v_fma_f32 v71, v95, v39, v23
	v_mul_f32_e32 v92, v56, v84
	v_fma_f32 v72, v92, v40, v24
	v_mul_f32_e32 v93, v57, v84
	v_fma_f32 v73, v93, v41, v25
	v_mul_f32_e32 v94, v58, v84
	v_fma_f32 v74, v94, v42, v26
	v_mul_f32_e32 v95, v59, v84
	v_fma_f32 v75, v95, v43, v27
	v_mul_f32_e32 v92, v60, v84
	v_fma_f32 v76, v92, v44, v28
	v_mul_f32_e32 v93, v61, v84
	v_fma_f32 v77, v93, v45, v29
	v_mul_f32_e32 v94, v62, v84
	v_fma_f32 v78, v94, v46, v30
	v_mul_f32_e32 v95, v63, v84
	v_fma_f32 v79, v95, v47, v31
	s_add_u32 s22, s18, s21
	s_addc_u32 s23, s19, 0
	v_cvt_pk_bf16_f32 v108, v64, v65
	v_cvt_pk_bf16_f32 v109, v66, v67
	v_cvt_pk_bf16_f32 v110, v68, v69
	v_cvt_pk_bf16_f32 v111, v70, v71
	v_cvt_pk_bf16_f32 v112, v72, v73
	v_cvt_pk_bf16_f32 v113, v74, v75
	v_cvt_pk_bf16_f32 v114, v76, v77
	v_cvt_pk_bf16_f32 v115, v78, v79
	global_store_dwordx4 v82, v[108:111], s[22:23]
	global_store_dwordx4 v82, v[112:115], s[22:23] offset:1024
.Lgro2_bend:
	s_mul_i32 s4, s14, 5
	s_add_u32 s13, s13, s4
	s_cmp_lt_u32 s13, 0x2800
	s_cbranch_scc1 .Lgro2_batch

.LBB0_929:
	s_andn2_b64 vcc, exec, s[2:3]
	s_cbranch_vccnz .LBB0_983
	v_readlane_b32 s10, v164, 0
	v_readlane_b32 s11, v162, 14
	v_lshrrev_b32_e32 v80, 6, v128
	v_and_b32_e32 v81, 63, v128
	v_readlane_b32 s16, v163, 13
	v_readlane_b32 s17, v163, 14
	v_readlane_b32 s18, v163, 15
	v_readlane_b32 s19, v163, 16
	v_readfirstlane_b32 s12, v80
	v_lshlrev_b32_e32 v82, 4, v81
	v_lshlrev_b32_e32 v83, 5, v81
	s_lshl_b32 s13, s10, 2
	s_add_u32 s13, s13, s12
	s_lshl_b32 s14, s11, 2
	s_mul_i32 s4, s34, 0x1b000
	s_add_u32 s6, s4, 0x5000
	s_add_u32 s7, s4, 0x6000

.LBB0_1112:
	v_readlane_b32 s10, v164, 0
	v_readlane_b32 s11, v162, 14
	v_lshrrev_b32_e32 v80, 6, v128
	v_and_b32_e32 v81, 63, v128
	v_readlane_b32 s16, v163, 13
	v_readlane_b32 s17, v163, 14
	v_readlane_b32 s18, v163, 15
	v_readlane_b32 s19, v163, 16
	v_readfirstlane_b32 s12, v80
	v_lshlrev_b32_e32 v82, 4, v81
	v_lshlrev_b32_e32 v83, 5, v81
	s_lshl_b32 s13, s10, 2
	s_add_u32 s13, s13, s12
	s_lshl_b32 s14, s11, 2
	s_mul_i32 s4, s34, 0x1b000
	s_add_u32 s6, s4, 0x8000
	s_mov_b32 s7, 0x1b000
	v_readlane_b32 s8, v164, 61
	v_readlane_b32 s9, v164, 62
.Lgro11_batch:
	s_mov_b32 s20, s13
	s_min_u32 s21, s20, 0x27ff
	s_lshl_b32 s21, s21, 11
	s_add_u32 s22, s86, s21
	s_addc_u32 s23, s87, 0
	global_load_dwordx4 v[168:171], v82, s[22:23]
	global_load_dwordx4 v[172:175], v82, s[22:23] offset:1024
	s_add_u32 s22, s78, s21
	s_addc_u32 s23, s79, 0
	global_load_dwordx4 v[176:179], v82, s[22:23]
	global_load_dwordx4 v[180:183], v82, s[22:23] offset:1024
	s_add_u32 s20, s20, s14
	s_min_u32 s21, s20, 0x27ff
	s_lshl_b32 s21, s21, 11
	s_add_u32 s22, s86, s21
	s_addc_u32 s23, s87, 0
	global_load_dwordx4 v[184:187], v82, s[22:23]
	global_load_dwordx4 v[188:191], v82, s[22:23] offset:1024
	s_add_u32 s22, s78, s21
	s_addc_u32 s23, s79, 0
	global_load_dwordx4 v[192:195], v82, s[22:23]
	global_load_dwordx4 v[196:199], v82, s[22:23] offset:1024
	s_add_u32 s20, s20, s14
	s_min_u32 s21, s20, 0x27ff
	s_lshl_b32 s21, s21, 11
	s_add_u32 s22, s86, s21
	s_addc_u32 s23, s87, 0
	global_load_dwordx4 v[200:203], v82, s[22:23]
	global_load_dwordx4 v[204:207], v82, s[22:23] offset:1024
	s_add_u32 s22, s78, s21
	s_addc_u32 s23, s79, 0
	global_load_dwordx4 v[208:211], v82, s[22:23]
	global_load_dwordx4 v[212:215], v82, s[22:23] offset:1024
	s_add_u32 s20, s20, s14
	s_min_u32 s21, s20, 0x27ff
	s_lshl_b32 s21, s21, 11
	s_add_u32 s22, s86, s21
	s_addc_u32 s23, s87, 0
	global_load_dwordx4 v[216:219], v82, s[22:23]
	global_load_dwordx4 v[220:223], v82, s[22:23] offset:1024
	s_add_u32 s22, s78, s21
	s_addc_u32 s23, s79, 0
	global_load_dwordx4 v[224:227], v82, s[22:23]
	global_load_dwordx4 v[228:231], v82, s[22:23] offset:1024
	s_add_u32 s20, s20, s14
	s_min_u32 s21, s20, 0x27ff
	s_lshl_b32 s21, s21, 11
	s_add_u32 s22, s86, s21
	s_addc_u32 s23, s87, 0
	global_load_dwordx4 v[232:235], v82, s[22:23]
	global_load_dwordx4 v[236:239], v82, s[22:23] offset:1024
	s_add_u32 s22, s78, s21
	s_addc_u32 s23, s79, 0
	global_load_dwordx4 v[240:243], v82, s[22:23]
	global_load_dwordx4 v[244:247], v82, s[22:23] offset:1024
	s_mov_b32 s15, -1
	s_mov_b32 s20, s13
	s_cmp_ge_u32 s20, 0x2800
	s_cbranch_scc1 .Lgro11_bend
	s_sub_u32 s4, s20, 0x2000
	s_lshr_b32 s4, s4, 10
	s_add_u32 s4, s4, 1
	s_cmp_lt_u32 s20, 0x2000
	s_cselect_b32 s4, 0, s4
	s_cmp_eq_u32 s4, s15
	s_cbranch_scc1 .Lgro11_r0_same
	s_mov_b32 s15, s4
	s_mul_i32 s4, s4, 0x9000
	s_add_u32 s32, s4, s6
	s_add_u32 s22, s16, s32
	s_addc_u32 s23, s17, 0
	global_load_dwordx4 v[0:3], v83, s[22:23]
	global_load_dwordx4 v[4:7], v83, s[22:23] offset:16
	global_load_dwordx4 v[8:11], v83, s[22:23] offset:2048
	global_load_dwordx4 v[12:15], v83, s[22:23] offset:2064
	s_cmp_lg_u32 s34, 0
	s_cbranch_scc1 .Lgro11_r0_novec
	s_add_u32 s32, s4, s7
	s_add_u32 s22, s16, s32
	s_addc_u32 s23, s17, 0
	global_load_dwordx4 v[16:19], v83, s[22:23]
	global_load_dwordx4 v[20:23], v83, s[22:23] offset:16
	global_load_dwordx4 v[24:27], v83, s[22:23] offset:2048
	global_load_dwordx4 v[28:31], v83, s[22:23] offset:2064
	s_add_u32 s22, s22, 0x1000
	s_addc_u32 s23, s23, 0
	global_load_dwordx4 v[32:35], v83, s[22:23]
	global_load_dwordx4 v[36:39], v83, s[22:23] offset:16
	global_load_dwordx4 v[40:43], v83, s[22:23] offset:2048
	global_load_dwordx4 v[44:47], v83, s[22:23] offset:2064
.Lgro11_r0_novec:
	s_waitcnt vmcnt(0)
	s_branch .Lgro11_r0_go

.Lgro11_r0_go:
	v_lshlrev_b32_e32 v48, 16, v168
	v_and_b32_e32 v49, 0xffff0000, v168
	v_lshlrev_b32_e32 v50, 16, v169
	v_and_b32_e32 v51, 0xffff0000, v169
	v_lshlrev_b32_e32 v52, 16, v170
	v_and_b32_e32 v53, 0xffff0000, v170
	v_lshlrev_b32_e32 v54, 16, v171
	v_and_b32_e32 v55, 0xffff0000, v171
	v_lshlrev_b32_e32 v56, 16, v172
	v_and_b32_e32 v57, 0xffff0000, v172
	v_lshlrev_b32_e32 v58, 16, v173
	v_and_b32_e32 v59, 0xffff0000, v173
	v_lshlrev_b32_e32 v60, 16, v174
	v_and_b32_e32 v61, 0xffff0000, v174
	v_lshlrev_b32_e32 v62, 16, v175
	v_and_b32_e32 v63, 0xffff0000, v175
	v_lshlrev_b32_e32 v64, 16, v176
	v_and_b32_e32 v65, 0xffff0000, v176
	v_lshlrev_b32_e32 v66, 16, v177
	v_and_b32_e32 v67, 0xffff0000, v177
	v_lshlrev_b32_e32 v68, 16, v178
	v_and_b32_e32 v69, 0xffff0000, v178
	v_lshlrev_b32_e32 v70, 16, v179
	v_and_b32_e32 v71, 0xffff0000, v179
	v_lshlrev_b32_e32 v72, 16, v180
	v_and_b32_e32 v73, 0xffff0000, v180
	v_lshlrev_b32_e32 v74, 16, v181
	v_and_b32_e32 v75, 0xffff0000, v181
	v_lshlrev_b32_e32 v76, 16, v182
	v_and_b32_e32 v77, 0xffff0000, v182
	v_lshlrev_b32_e32 v78, 16, v183
	v_and_b32_e32 v79, 0xffff0000, v183
	v_mul_f32_e32 v88, v64, v64
	v_mul_f32_e32 v89, v65, v65
	v_mul_f32_e32 v90, v66, v66
	v_mul_f32_e32 v91, v67, v67
	v_fmac_f32_e32 v88, v68, v68
	v_fmac_f32_e32 v89, v69, v69
	v_fmac_f32_e32 v90, v70, v70
	v_fmac_f32_e32 v91, v71, v71
	v_fmac_f32_e32 v88, v72, v72
	v_fmac_f32_e32 v89, v73, v73
	v_fmac_f32_e32 v90, v74, v74
	v_fmac_f32_e32 v91, v75, v75
	v_fmac_f32_e32 v88, v76, v76
	v_fmac_f32_e32 v89, v77, v77
	v_fmac_f32_e32 v90, v78, v78
	v_fmac_f32_e32 v91, v79, v79
	v_add_f32_e32 v88, v88, v89
	v_add_f32_e32 v90, v90, v91
	v_add_f32_e32 v84, v88, v90
	s_nop 1
	v_add_f32_dpp v84, v84, v84 quad_perm:[1,0,3,2] row_mask:0xf bank_mask:0xf bound_ctrl:1
	s_nop 1
	v_add_f32_dpp v84, v84, v84 quad_perm:[2,3,0,1] row_mask:0xf bank_mask:0xf bound_ctrl:1
	s_nop 1
	v_add_f32_dpp v84, v84, v84 row_half_mirror row_mask:0xf bank_mask:0xf bound_ctrl:1
	s_nop 1
	v_add_f32_dpp v84, v84, v84 row_mirror row_mask:0xf bank_mask:0xf bound_ctrl:1
	s_nop 0
	v_readlane_b32 s44, v84, 0
	v_readlane_b32 s46, v84, 16
	v_readlane_b32 s48, v84, 32
	v_readlane_b32 s50, v84, 48
	s_nop 0
	v_mov_b32_e32 v85, s44
	v_mov_b32_e32 v86, s48
	v_add_f32_e32 v85, s46, v85
	v_add_f32_e32 v86, s50, v86
	v_add_f32_e32 v84, v85, v86
	v_fmamk_f32 v84, v84, 0x3a800000, v130
	v_rsq_f32_e32 v84, v84
	s_nop 0
	v_mul_f32_e32 v92, v84, v64
	v_fmac_f32_e32 v48, v0, v92
	v_mul_f32_e32 v93, v84, v65
	v_fmac_f32_e32 v49, v1, v93
	v_mul_f32_e32 v94, v84, v66
	v_fmac_f32_e32 v50, v2, v94
	v_mul_f32_e32 v95, v84, v67
	v_fmac_f32_e32 v51, v3, v95
	v_mul_f32_e32 v92, v84, v68
	v_fmac_f32_e32 v52, v4, v92
	v_mul_f32_e32 v93, v84, v69
	v_fmac_f32_e32 v53, v5, v93
	v_mul_f32_e32 v94, v84, v70
	v_fmac_f32_e32 v54, v6, v94
	v_mul_f32_e32 v95, v84, v71
	v_fmac_f32_e32 v55, v7, v95
	v_mul_f32_e32 v92, v84, v72
	v_fmac_f32_e32 v56, v8, v92
	v_mul_f32_e32 v93, v84, v73
	v_fmac_f32_e32 v57, v9, v93
	v_mul_f32_e32 v94, v84, v74
	v_fmac_f32_e32 v58, v10, v94
	v_mul_f32_e32 v95, v84, v75
	v_fmac_f32_e32 v59, v11, v95
	v_mul_f32_e32 v92, v84, v76
	v_fmac_f32_e32 v60, v12, v92
	v_mul_f32_e32 v93, v84, v77
	v_fmac_f32_e32 v61, v13, v93
	v_mul_f32_e32 v94, v84, v78
	v_fmac_f32_e32 v62, v14, v94
	v_mul_f32_e32 v95, v84, v79
	v_fmac_f32_e32 v63, v15, v95
	s_lshl_b32 s21, s20, 11
	s_cmp_lg_u32 s34, 0
	s_cbranch_scc1 .Lgro11_r0_fin
	s_add_u32 s22, s86, s21
	s_addc_u32 s23, s87, 0
	v_cvt_pk_bf16_f32 v100, v48, v49
	v_cvt_pk_bf16_f32 v101, v50, v51
	v_cvt_pk_bf16_f32 v102, v52, v53
	v_cvt_pk_bf16_f32 v103, v54, v55
	v_cvt_pk_bf16_f32 v104, v56, v57
	v_cvt_pk_bf16_f32 v105, v58, v59
	v_cvt_pk_bf16_f32 v106, v60, v61
	v_cvt_pk_bf16_f32 v107, v62, v63
	global_store_dwordx4 v82, v[100:103], s[22:23]
	global_store_dwordx4 v82, v[104:107], s[22:23] offset:1024
	v_mul_f32_e32 v88, v48, v48
	v_mul_f32_e32 v89, v49, v49
	v_mul_f32_e32 v90, v50, v50
	v_mul_f32_e32 v91, v51, v51
	v_fmac_f32_e32 v88, v52, v52
	v_fmac_f32_e32 v89, v53, v53
	v_fmac_f32_e32 v90, v54, v54
	v_fmac_f32_e32 v91, v55, v55
	v_fmac_f32_e32 v88, v56, v56
	v_fmac_f32_e32 v89, v57, v57
	v_fmac_f32_e32 v90, v58, v58
	v_fmac_f32_e32 v91, v59, v59
	v_fmac_f32_e32 v88, v60, v60
	v_fmac_f32_e32 v89, v61, v61
	v_fmac_f32_e32 v90, v62, v62
	v_fmac_f32_e32 v91, v63, v63
	v_add_f32_e32 v88, v88, v89
	v_add_f32_e32 v90, v90, v91
	v_add_f32_e32 v84, v88, v90
	s_nop 1
	v_add_f32_dpp v84, v84, v84 quad_perm:[1,0,3,2] row_mask:0xf bank_mask:0xf bound_ctrl:1
	s_nop 1
	v_add_f32_dpp v84, v84, v84 quad_perm:[2,3,0,1] row_mask:0xf bank_mask:0xf bound_ctrl:1
	s_nop 1
	v_add_f32_dpp v84, v84, v84 row_half_mirror row_mask:0xf bank_mask:0xf bound_ctrl:1
	s_nop 1
	v_add_f32_dpp v84, v84, v84 row_mirror row_mask:0xf bank_mask:0xf bound_ctrl:1
	s_nop 0
	v_readlane_b32 s44, v84, 0
	v_readlane_b32 s46, v84, 16
	v_readlane_b32 s48, v84, 32
	v_readlane_b32 s50, v84, 48
	s_nop 0
	v_mov_b32_e32 v85, s44
	v_mov_b32_e32 v86, s48
	v_add_f32_e32 v85, s46, v85
	v_add_f32_e32 v86, s50, v86
	v_add_f32_e32 v84, v85, v86
	v_fmamk_f32 v84, v84, 0x3a800000, v130
	v_rsq_f32_e32 v84, v84
	s_nop 0
	v_mul_f32_e32 v92, v48, v84
	v_fma_f32 v64, v92, v32, v16
	v_mul_f32_e32 v93, v49, v84
	v_fma_f32 v65, v93, v33, v17
	v_mul_f32_e32 v94, v50, v84
	v_fma_f32 v66, v94, v34, v18
	v_mul_f32_e32 v95, v51, v84
	v_fma_f32 v67, v95, v35, v19
	v_mul_f32_e32 v92, v52, v84
	v_fma_f32 v68, v92, v36, v20
	v_mul_f32_e32 v93, v53, v84
	v_fma_f32 v69, v93, v37, v21
	v_mul_f32_e32 v94, v54, v84
	v_fma_f32 v70, v94, v38, v22
	v_mul_f32_e32 v95, v55, v84
	v_fma_f32 v71, v95, v39, v23
	v_mul_f32_e32 v92, v56, v84
	v_fma_f32 v72, v92, v40, v24
	v_mul_f32_e32 v93, v57, v84
	v_fma_f32 v73, v93, v41, v25
	v_mul_f32_e32 v94, v58, v84
	v_fma_f32 v74, v94, v42, v26
	v_mul_f32_e32 v95, v59, v84
	v_fma_f32 v75, v95, v43, v27
	v_mul_f32_e32 v92, v60, v84
	v_fma_f32 v76, v92, v44, v28
	v_mul_f32_e32 v93, v61, v84
	v_fma_f32 v77, v93, v45, v29
	v_mul_f32_e32 v94, v62, v84
	v_fma_f32 v78, v94, v46, v30
	v_mul_f32_e32 v95, v63, v84
	v_fma_f32 v79, v95, v47, v31
	s_add_u32 s22, s18, s21
	s_addc_u32 s23, s19, 0
	v_cvt_pk_bf16_f32 v108, v64, v65
	v_cvt_pk_bf16_f32 v109, v66, v67
	v_cvt_pk_bf16_f32 v110, v68, v69
	v_cvt_pk_bf16_f32 v111, v70, v71
	v_cvt_pk_bf16_f32 v112, v72, v73
	v_cvt_pk_bf16_f32 v113, v74, v75
	v_cvt_pk_bf16_f32 v114, v76, v77
	v_cvt_pk_bf16_f32 v115, v78, v79
	global_store_dwordx4 v82, v[108:111], s[22:23]
	global_store_dwordx4 v82, v[112:115], s[22:23] offset:1024
	s_branch .Lgro11_r0_done
.Lgro11_r0_fin:
	s_lshl_b32 s21, s20, 12
	s_add_u32 s22, s8, s21
	s_addc_u32 s23, s9, 0
	global_store_dwordx4 v83, v[48:51], s[22:23]
	global_store_dwordx4 v83, v[52:55], s[22:23] offset:16
	global_store_dwordx4 v83, v[56:59], s[22:23] offset:2048
	global_store_dwordx4 v83, v[60:63], s[22:23] offset:2064
.Lgro11_r0_done:
	s_add_u32 s20, s20, s14
	s_cmp_ge_u32 s20, 0x2800
	s_cbranch_scc1 .Lgro11_bend
	s_sub_u32 s4, s20, 0x2000
	s_lshr_b32 s4, s4, 10
	s_add_u32 s4, s4, 1
	s_cmp_lt_u32 s20, 0x2000
	s_cselect_b32 s4, 0, s4
	s_cmp_eq_u32 s4, s15
	s_cbranch_scc1 .Lgro11_r1_same
	s_mov_b32 s15, s4
	s_mul_i32 s4, s4, 0x9000
	s_add_u32 s32, s4, s6
	s_add_u32 s22, s16, s32
	s_addc_u32 s23, s17, 0
	global_load_dwordx4 v[0:3], v83, s[22:23]
	global_load_dwordx4 v[4:7], v83, s[22:23] offset:16
	global_load_dwordx4 v[8:11], v83, s[22:23] offset:2048
	global_load_dwordx4 v[12:15], v83, s[22:23] offset:2064
	s_cmp_lg_u32 s34, 0
	s_cbranch_scc1 .Lgro11_r1_novec
	s_add_u32 s32, s4, s7
	s_add_u32 s22, s16, s32
	s_addc_u32 s23, s17, 0
	global_load_dwordx4 v[16:19], v83, s[22:23]
	global_load_dwordx4 v[20:23], v83, s[22:23] offset:16
	global_load_dwordx4 v[24:27], v83, s[22:23] offset:2048
	global_load_dwordx4 v[28:31], v83, s[22:23] offset:2064
	s_add_u32 s22, s22, 0x1000
	s_addc_u32 s23, s23, 0
	global_load_dwordx4 v[32:35], v83, s[22:23]
	global_load_dwordx4 v[36:39], v83, s[22:23] offset:16
	global_load_dwordx4 v[40:43], v83, s[22:23] offset:2048
	global_load_dwordx4 v[44:47], v83, s[22:23] offset:2064

.Lgro11_r1_go:
	v_lshlrev_b32_e32 v48, 16, v184
	v_and_b32_e32 v49, 0xffff0000, v184
	v_lshlrev_b32_e32 v50, 16, v185
	v_and_b32_e32 v51, 0xffff0000, v185
	v_lshlrev_b32_e32 v52, 16, v186
	v_and_b32_e32 v53, 0xffff0000, v186
	v_lshlrev_b32_e32 v54, 16, v187
	v_and_b32_e32 v55, 0xffff0000, v187
	v_lshlrev_b32_e32 v56, 16, v188
	v_and_b32_e32 v57, 0xffff0000, v188
	v_lshlrev_b32_e32 v58, 16, v189
	v_and_b32_e32 v59, 0xffff0000, v189
	v_lshlrev_b32_e32 v60, 16, v190
	v_and_b32_e32 v61, 0xffff0000, v190
	v_lshlrev_b32_e32 v62, 16, v191
	v_and_b32_e32 v63, 0xffff0000, v191
	v_lshlrev_b32_e32 v64, 16, v192
	v_and_b32_e32 v65, 0xffff0000, v192
	v_lshlrev_b32_e32 v66, 16, v193
	v_and_b32_e32 v67, 0xffff0000, v193
	v_lshlrev_b32_e32 v68, 16, v194
	v_and_b32_e32 v69, 0xffff0000, v194
	v_lshlrev_b32_e32 v70, 16, v195
	v_and_b32_e32 v71, 0xffff0000, v195
	v_lshlrev_b32_e32 v72, 16, v196
	v_and_b32_e32 v73, 0xffff0000, v196
	v_lshlrev_b32_e32 v74, 16, v197
	v_and_b32_e32 v75, 0xffff0000, v197
	v_lshlrev_b32_e32 v76, 16, v198
	v_and_b32_e32 v77, 0xffff0000, v198
	v_lshlrev_b32_e32 v78, 16, v199
	v_and_b32_e32 v79, 0xffff0000, v199
	v_mul_f32_e32 v88, v64, v64
	v_mul_f32_e32 v89, v65, v65
	v_mul_f32_e32 v90, v66, v66
	v_mul_f32_e32 v91, v67, v67
	v_fmac_f32_e32 v88, v68, v68
	v_fmac_f32_e32 v89, v69, v69
	v_fmac_f32_e32 v90, v70, v70
	v_fmac_f32_e32 v91, v71, v71
	v_fmac_f32_e32 v88, v72, v72
	v_fmac_f32_e32 v89, v73, v73
	v_fmac_f32_e32 v90, v74, v74
	v_fmac_f32_e32 v91, v75, v75
	v_fmac_f32_e32 v88, v76, v76
	v_fmac_f32_e32 v89, v77, v77
	v_fmac_f32_e32 v90, v78, v78
	v_fmac_f32_e32 v91, v79, v79
	v_add_f32_e32 v88, v88, v89
	v_add_f32_e32 v90, v90, v91
	v_add_f32_e32 v84, v88, v90
	s_nop 1
	v_add_f32_dpp v84, v84, v84 quad_perm:[1,0,3,2] row_mask:0xf bank_mask:0xf bound_ctrl:1
	s_nop 1
	v_add_f32_dpp v84, v84, v84 quad_perm:[2,3,0,1] row_mask:0xf bank_mask:0xf bound_ctrl:1
	s_nop 1
	v_add_f32_dpp v84, v84, v84 row_half_mirror row_mask:0xf bank_mask:0xf bound_ctrl:1
	s_nop 1
	v_add_f32_dpp v84, v84, v84 row_mirror row_mask:0xf bank_mask:0xf bound_ctrl:1
	s_nop 0
	v_readlane_b32 s44, v84, 0
	v_readlane_b32 s46, v84, 16
	v_readlane_b32 s48, v84, 32
	v_readlane_b32 s50, v84, 48
	s_nop 0
	v_mov_b32_e32 v85, s44
	v_mov_b32_e32 v86, s48
	v_add_f32_e32 v85, s46, v85
	v_add_f32_e32 v86, s50, v86
	v_add_f32_e32 v84, v85, v86
	v_fmamk_f32 v84, v84, 0x3a800000, v130
	v_rsq_f32_e32 v84, v84
	s_nop 0
	v_mul_f32_e32 v92, v84, v64
	v_fmac_f32_e32 v48, v0, v92
	v_mul_f32_e32 v93, v84, v65
	v_fmac_f32_e32 v49, v1, v93
	v_mul_f32_e32 v94, v84, v66
	v_fmac_f32_e32 v50, v2, v94
	v_mul_f32_e32 v95, v84, v67
	v_fmac_f32_e32 v51, v3, v95
	v_mul_f32_e32 v92, v84, v68
	v_fmac_f32_e32 v52, v4, v92
	v_mul_f32_e32 v93, v84, v69
	v_fmac_f32_e32 v53, v5, v93
	v_mul_f32_e32 v94, v84, v70
	v_fmac_f32_e32 v54, v6, v94
	v_mul_f32_e32 v95, v84, v71
	v_fmac_f32_e32 v55, v7, v95
	v_mul_f32_e32 v92, v84, v72
	v_fmac_f32_e32 v56, v8, v92
	v_mul_f32_e32 v93, v84, v73
	v_fmac_f32_e32 v57, v9, v93
	v_mul_f32_e32 v94, v84, v74
	v_fmac_f32_e32 v58, v10, v94
	v_mul_f32_e32 v95, v84, v75
	v_fmac_f32_e32 v59, v11, v95
	v_mul_f32_e32 v92, v84, v76
	v_fmac_f32_e32 v60, v12, v92
	v_mul_f32_e32 v93, v84, v77
	v_fmac_f32_e32 v61, v13, v93
	v_mul_f32_e32 v94, v84, v78
	v_fmac_f32_e32 v62, v14, v94
	v_mul_f32_e32 v95, v84, v79
	v_fmac_f32_e32 v63, v15, v95
	s_lshl_b32 s21, s20, 11
	s_cmp_lg_u32 s34, 0
	s_cbranch_scc1 .Lgro11_r1_fin
	s_add_u32 s22, s86, s21
	s_addc_u32 s23, s87, 0
	v_cvt_pk_bf16_f32 v100, v48, v49
	v_cvt_pk_bf16_f32 v101, v50, v51
	v_cvt_pk_bf16_f32 v102, v52, v53
	v_cvt_pk_bf16_f32 v103, v54, v55
	v_cvt_pk_bf16_f32 v104, v56, v57
	v_cvt_pk_bf16_f32 v105, v58, v59
	v_cvt_pk_bf16_f32 v106, v60, v61
	v_cvt_pk_bf16_f32 v107, v62, v63
	global_store_dwordx4 v82, v[100:103], s[22:23]
	global_store_dwordx4 v82, v[104:107], s[22:23] offset:1024
	v_mul_f32_e32 v88, v48, v48
	v_mul_f32_e32 v89, v49, v49
	v_mul_f32_e32 v90, v50, v50
	v_mul_f32_e32 v91, v51, v51
	v_fmac_f32_e32 v88, v52, v52
	v_fmac_f32_e32 v89, v53, v53
	v_fmac_f32_e32 v90, v54, v54
	v_fmac_f32_e32 v91, v55, v55
	v_fmac_f32_e32 v88, v56, v56
	v_fmac_f32_e32 v89, v57, v57
	v_fmac_f32_e32 v90, v58, v58
	v_fmac_f32_e32 v91, v59, v59
	v_fmac_f32_e32 v88, v60, v60
	v_fmac_f32_e32 v89, v61, v61
	v_fmac_f32_e32 v90, v62, v62
	v_fmac_f32_e32 v91, v63, v63
	v_add_f32_e32 v88, v88, v89
	v_add_f32_e32 v90, v90, v91
	v_add_f32_e32 v84, v88, v90
	s_nop 1
	v_add_f32_dpp v84, v84, v84 quad_perm:[1,0,3,2] row_mask:0xf bank_mask:0xf bound_ctrl:1
	s_nop 1
	v_add_f32_dpp v84, v84, v84 quad_perm:[2,3,0,1] row_mask:0xf bank_mask:0xf bound_ctrl:1
	s_nop 1
	v_add_f32_dpp v84, v84, v84 row_half_mirror row_mask:0xf bank_mask:0xf bound_ctrl:1
	s_nop 1
	v_add_f32_dpp v84, v84, v84 row_mirror row_mask:0xf bank_mask:0xf bound_ctrl:1
	s_nop 0
	v_readlane_b32 s44, v84, 0
	v_readlane_b32 s46, v84, 16
	v_readlane_b32 s48, v84, 32
	v_readlane_b32 s50, v84, 48
	s_nop 0
	v_mov_b32_e32 v85, s44
	v_mov_b32_e32 v86, s48
	v_add_f32_e32 v85, s46, v85
	v_add_f32_e32 v86, s50, v86
	v_add_f32_e32 v84, v85, v86
	v_fmamk_f32 v84, v84, 0x3a800000, v130
	v_rsq_f32_e32 v84, v84
	s_nop 0
	v_mul_f32_e32 v92, v48, v84
	v_fma_f32 v64, v92, v32, v16
	v_mul_f32_e32 v93, v49, v84
	v_fma_f32 v65, v93, v33, v17
	v_mul_f32_e32 v94, v50, v84
	v_fma_f32 v66, v94, v34, v18
	v_mul_f32_e32 v95, v51, v84
	v_fma_f32 v67, v95, v35, v19
	v_mul_f32_e32 v92, v52, v84
	v_fma_f32 v68, v92, v36, v20
	v_mul_f32_e32 v93, v53, v84
	v_fma_f32 v69, v93, v37, v21
	v_mul_f32_e32 v94, v54, v84
	v_fma_f32 v70, v94, v38, v22
	v_mul_f32_e32 v95, v55, v84
	v_fma_f32 v71, v95, v39, v23
	v_mul_f32_e32 v92, v56, v84
	v_fma_f32 v72, v92, v40, v24
	v_mul_f32_e32 v93, v57, v84
	v_fma_f32 v73, v93, v41, v25
	v_mul_f32_e32 v94, v58, v84
	v_fma_f32 v74, v94, v42, v26
	v_mul_f32_e32 v95, v59, v84
	v_fma_f32 v75, v95, v43, v27
	v_mul_f32_e32 v92, v60, v84
	v_fma_f32 v76, v92, v44, v28
	v_mul_f32_e32 v93, v61, v84
	v_fma_f32 v77, v93, v45, v29
	v_mul_f32_e32 v94, v62, v84
	v_fma_f32 v78, v94, v46, v30
	v_mul_f32_e32 v95, v63, v84
	v_fma_f32 v79, v95, v47, v31
	s_add_u32 s22, s18, s21
	s_addc_u32 s23, s19, 0
	v_cvt_pk_bf16_f32 v108, v64, v65
	v_cvt_pk_bf16_f32 v109, v66, v67
	v_cvt_pk_bf16_f32 v110, v68, v69
	v_cvt_pk_bf16_f32 v111, v70, v71
	v_cvt_pk_bf16_f32 v112, v72, v73
	v_cvt_pk_bf16_f32 v113, v74, v75
	v_cvt_pk_bf16_f32 v114, v76, v77
	v_cvt_pk_bf16_f32 v115, v78, v79
	global_store_dwordx4 v82, v[108:111], s[22:23]
	global_store_dwordx4 v82, v[112:115], s[22:23] offset:1024
	s_branch .Lgro11_r1_done

.Lgro11_r2_go:
	v_lshlrev_b32_e32 v48, 16, v200
	v_and_b32_e32 v49, 0xffff0000, v200
	v_lshlrev_b32_e32 v50, 16, v201
	v_and_b32_e32 v51, 0xffff0000, v201
	v_lshlrev_b32_e32 v52, 16, v202
	v_and_b32_e32 v53, 0xffff0000, v202
	v_lshlrev_b32_e32 v54, 16, v203
	v_and_b32_e32 v55, 0xffff0000, v203
	v_lshlrev_b32_e32 v56, 16, v204
	v_and_b32_e32 v57, 0xffff0000, v204
	v_lshlrev_b32_e32 v58, 16, v205
	v_and_b32_e32 v59, 0xffff0000, v205
	v_lshlrev_b32_e32 v60, 16, v206
	v_and_b32_e32 v61, 0xffff0000, v206
	v_lshlrev_b32_e32 v62, 16, v207
	v_and_b32_e32 v63, 0xffff0000, v207
	v_lshlrev_b32_e32 v64, 16, v208
	v_and_b32_e32 v65, 0xffff0000, v208
	v_lshlrev_b32_e32 v66, 16, v209
	v_and_b32_e32 v67, 0xffff0000, v209
	v_lshlrev_b32_e32 v68, 16, v210
	v_and_b32_e32 v69, 0xffff0000, v210
	v_lshlrev_b32_e32 v70, 16, v211
	v_and_b32_e32 v71, 0xffff0000, v211
	v_lshlrev_b32_e32 v72, 16, v212
	v_and_b32_e32 v73, 0xffff0000, v212
	v_lshlrev_b32_e32 v74, 16, v213
	v_and_b32_e32 v75, 0xffff0000, v213
	v_lshlrev_b32_e32 v76, 16, v214
	v_and_b32_e32 v77, 0xffff0000, v214
	v_lshlrev_b32_e32 v78, 16, v215
	v_and_b32_e32 v79, 0xffff0000, v215
	v_mul_f32_e32 v88, v64, v64
	v_mul_f32_e32 v89, v65, v65
	v_mul_f32_e32 v90, v66, v66
	v_mul_f32_e32 v91, v67, v67
	v_fmac_f32_e32 v88, v68, v68
	v_fmac_f32_e32 v89, v69, v69
	v_fmac_f32_e32 v90, v70, v70
	v_fmac_f32_e32 v91, v71, v71
	v_fmac_f32_e32 v88, v72, v72
	v_fmac_f32_e32 v89, v73, v73
	v_fmac_f32_e32 v90, v74, v74
	v_fmac_f32_e32 v91, v75, v75
	v_fmac_f32_e32 v88, v76, v76
	v_fmac_f32_e32 v89, v77, v77
	v_fmac_f32_e32 v90, v78, v78
	v_fmac_f32_e32 v91, v79, v79
	v_add_f32_e32 v88, v88, v89
	v_add_f32_e32 v90, v90, v91
	v_add_f32_e32 v84, v88, v90
	s_nop 1
	v_add_f32_dpp v84, v84, v84 quad_perm:[1,0,3,2] row_mask:0xf bank_mask:0xf bound_ctrl:1
	s_nop 1
	v_add_f32_dpp v84, v84, v84 quad_perm:[2,3,0,1] row_mask:0xf bank_mask:0xf bound_ctrl:1
	s_nop 1
	v_add_f32_dpp v84, v84, v84 row_half_mirror row_mask:0xf bank_mask:0xf bound_ctrl:1
	s_nop 1
	v_add_f32_dpp v84, v84, v84 row_mirror row_mask:0xf bank_mask:0xf bound_ctrl:1
	s_nop 0
	v_readlane_b32 s44, v84, 0
	v_readlane_b32 s46, v84, 16
	v_readlane_b32 s48, v84, 32
	v_readlane_b32 s50, v84, 48
	s_nop 0
	v_mov_b32_e32 v85, s44
	v_mov_b32_e32 v86, s48
	v_add_f32_e32 v85, s46, v85
	v_add_f32_e32 v86, s50, v86
	v_add_f32_e32 v84, v85, v86
	v_fmamk_f32 v84, v84, 0x3a800000, v130
	v_rsq_f32_e32 v84, v84
	s_nop 0
	v_mul_f32_e32 v92, v84, v64
	v_fmac_f32_e32 v48, v0, v92
	v_mul_f32_e32 v93, v84, v65
	v_fmac_f32_e32 v49, v1, v93
	v_mul_f32_e32 v94, v84, v66
	v_fmac_f32_e32 v50, v2, v94
	v_mul_f32_e32 v95, v84, v67
	v_fmac_f32_e32 v51, v3, v95
	v_mul_f32_e32 v92, v84, v68
	v_fmac_f32_e32 v52, v4, v92
	v_mul_f32_e32 v93, v84, v69
	v_fmac_f32_e32 v53, v5, v93
	v_mul_f32_e32 v94, v84, v70
	v_fmac_f32_e32 v54, v6, v94
	v_mul_f32_e32 v95, v84, v71
	v_fmac_f32_e32 v55, v7, v95
	v_mul_f32_e32 v92, v84, v72
	v_fmac_f32_e32 v56, v8, v92
	v_mul_f32_e32 v93, v84, v73
	v_fmac_f32_e32 v57, v9, v93
	v_mul_f32_e32 v94, v84, v74
	v_fmac_f32_e32 v58, v10, v94
	v_mul_f32_e32 v95, v84, v75
	v_fmac_f32_e32 v59, v11, v95
	v_mul_f32_e32 v92, v84, v76
	v_fmac_f32_e32 v60, v12, v92
	v_mul_f32_e32 v93, v84, v77
	v_fmac_f32_e32 v61, v13, v93
	v_mul_f32_e32 v94, v84, v78
	v_fmac_f32_e32 v62, v14, v94
	v_mul_f32_e32 v95, v84, v79
	v_fmac_f32_e32 v63, v15, v95
	s_lshl_b32 s21, s20, 11
	s_cmp_lg_u32 s34, 0
	s_cbranch_scc1 .Lgro11_r2_fin
	s_add_u32 s22, s86, s21
	s_addc_u32 s23, s87, 0
	v_cvt_pk_bf16_f32 v100, v48, v49
	v_cvt_pk_bf16_f32 v101, v50, v51
	v_cvt_pk_bf16_f32 v102, v52, v53
	v_cvt_pk_bf16_f32 v103, v54, v55
	v_cvt_pk_bf16_f32 v104, v56, v57
	v_cvt_pk_bf16_f32 v105, v58, v59
	v_cvt_pk_bf16_f32 v106, v60, v61
	v_cvt_pk_bf16_f32 v107, v62, v63
	global_store_dwordx4 v82, v[100:103], s[22:23]
	global_store_dwordx4 v82, v[104:107], s[22:23] offset:1024
	v_mul_f32_e32 v88, v48, v48
	v_mul_f32_e32 v89, v49, v49
	v_mul_f32_e32 v90, v50, v50
	v_mul_f32_e32 v91, v51, v51
	v_fmac_f32_e32 v88, v52, v52
	v_fmac_f32_e32 v89, v53, v53
	v_fmac_f32_e32 v90, v54, v54
	v_fmac_f32_e32 v91, v55, v55
	v_fmac_f32_e32 v88, v56, v56
	v_fmac_f32_e32 v89, v57, v57
	v_fmac_f32_e32 v90, v58, v58
	v_fmac_f32_e32 v91, v59, v59
	v_fmac_f32_e32 v88, v60, v60
	v_fmac_f32_e32 v89, v61, v61
	v_fmac_f32_e32 v90, v62, v62
	v_fmac_f32_e32 v91, v63, v63
	v_add_f32_e32 v88, v88, v89
	v_add_f32_e32 v90, v90, v91
	v_add_f32_e32 v84, v88, v90
	s_nop 1
	v_add_f32_dpp v84, v84, v84 quad_perm:[1,0,3,2] row_mask:0xf bank_mask:0xf bound_ctrl:1
	s_nop 1
	v_add_f32_dpp v84, v84, v84 quad_perm:[2,3,0,1] row_mask:0xf bank_mask:0xf bound_ctrl:1
	s_nop 1
	v_add_f32_dpp v84, v84, v84 row_half_mirror row_mask:0xf bank_mask:0xf bound_ctrl:1
	s_nop 1
	v_add_f32_dpp v84, v84, v84 row_mirror row_mask:0xf bank_mask:0xf bound_ctrl:1
	s_nop 0
	v_readlane_b32 s44, v84, 0
	v_readlane_b32 s46, v84, 16
	v_readlane_b32 s48, v84, 32
	v_readlane_b32 s50, v84, 48
	s_nop 0
	v_mov_b32_e32 v85, s44
	v_mov_b32_e32 v86, s48
	v_add_f32_e32 v85, s46, v85
	v_add_f32_e32 v86, s50, v86
	v_add_f32_e32 v84, v85, v86
	v_fmamk_f32 v84, v84, 0x3a800000, v130
	v_rsq_f32_e32 v84, v84
	s_nop 0
	v_mul_f32_e32 v92, v48, v84
	v_fma_f32 v64, v92, v32, v16
	v_mul_f32_e32 v93, v49, v84
	v_fma_f32 v65, v93, v33, v17
	v_mul_f32_e32 v94, v50, v84
	v_fma_f32 v66, v94, v34, v18
	v_mul_f32_e32 v95, v51, v84
	v_fma_f32 v67, v95, v35, v19
	v_mul_f32_e32 v92, v52, v84
	v_fma_f32 v68, v92, v36, v20
	v_mul_f32_e32 v93, v53, v84
	v_fma_f32 v69, v93, v37, v21
	v_mul_f32_e32 v94, v54, v84
	v_fma_f32 v70, v94, v38, v22
	v_mul_f32_e32 v95, v55, v84
	v_fma_f32 v71, v95, v39, v23
	v_mul_f32_e32 v92, v56, v84
	v_fma_f32 v72, v92, v40, v24
	v_mul_f32_e32 v93, v57, v84
	v_fma_f32 v73, v93, v41, v25
	v_mul_f32_e32 v94, v58, v84
	v_fma_f32 v74, v94, v42, v26
	v_mul_f32_e32 v95, v59, v84
	v_fma_f32 v75, v95, v43, v27
	v_mul_f32_e32 v92, v60, v84
	v_fma_f32 v76, v92, v44, v28
	v_mul_f32_e32 v93, v61, v84
	v_fma_f32 v77, v93, v45, v29
	v_mul_f32_e32 v94, v62, v84
	v_fma_f32 v78, v94, v46, v30
	v_mul_f32_e32 v95, v63, v84
	v_fma_f32 v79, v95, v47, v31
	s_add_u32 s22, s18, s21
	s_addc_u32 s23, s19, 0
	v_cvt_pk_bf16_f32 v108, v64, v65
	v_cvt_pk_bf16_f32 v109, v66, v67
	v_cvt_pk_bf16_f32 v110, v68, v69
	v_cvt_pk_bf16_f32 v111, v70, v71
	v_cvt_pk_bf16_f32 v112, v72, v73
	v_cvt_pk_bf16_f32 v113, v74, v75
	v_cvt_pk_bf16_f32 v114, v76, v77
	v_cvt_pk_bf16_f32 v115, v78, v79
	global_store_dwordx4 v82, v[108:111], s[22:23]
	global_store_dwordx4 v82, v[112:115], s[22:23] offset:1024
	s_branch .Lgro11_r2_done

.Lgro11_r3_go:
	v_lshlrev_b32_e32 v48, 16, v216
	v_and_b32_e32 v49, 0xffff0000, v216
	v_lshlrev_b32_e32 v50, 16, v217
	v_and_b32_e32 v51, 0xffff0000, v217
	v_lshlrev_b32_e32 v52, 16, v218
	v_and_b32_e32 v53, 0xffff0000, v218
	v_lshlrev_b32_e32 v54, 16, v219
	v_and_b32_e32 v55, 0xffff0000, v219
	v_lshlrev_b32_e32 v56, 16, v220
	v_and_b32_e32 v57, 0xffff0000, v220
	v_lshlrev_b32_e32 v58, 16, v221
	v_and_b32_e32 v59, 0xffff0000, v221
	v_lshlrev_b32_e32 v60, 16, v222
	v_and_b32_e32 v61, 0xffff0000, v222
	v_lshlrev_b32_e32 v62, 16, v223
	v_and_b32_e32 v63, 0xffff0000, v223
	v_lshlrev_b32_e32 v64, 16, v224
	v_and_b32_e32 v65, 0xffff0000, v224
	v_lshlrev_b32_e32 v66, 16, v225
	v_and_b32_e32 v67, 0xffff0000, v225
	v_lshlrev_b32_e32 v68, 16, v226
	v_and_b32_e32 v69, 0xffff0000, v226
	v_lshlrev_b32_e32 v70, 16, v227
	v_and_b32_e32 v71, 0xffff0000, v227
	v_lshlrev_b32_e32 v72, 16, v228
	v_and_b32_e32 v73, 0xffff0000, v228
	v_lshlrev_b32_e32 v74, 16, v229
	v_and_b32_e32 v75, 0xffff0000, v229
	v_lshlrev_b32_e32 v76, 16, v230
	v_and_b32_e32 v77, 0xffff0000, v230
	v_lshlrev_b32_e32 v78, 16, v231
	v_and_b32_e32 v79, 0xffff0000, v231
	v_mul_f32_e32 v88, v64, v64
	v_mul_f32_e32 v89, v65, v65
	v_mul_f32_e32 v90, v66, v66
	v_mul_f32_e32 v91, v67, v67
	v_fmac_f32_e32 v88, v68, v68
	v_fmac_f32_e32 v89, v69, v69
	v_fmac_f32_e32 v90, v70, v70
	v_fmac_f32_e32 v91, v71, v71
	v_fmac_f32_e32 v88, v72, v72
	v_fmac_f32_e32 v89, v73, v73
	v_fmac_f32_e32 v90, v74, v74
	v_fmac_f32_e32 v91, v75, v75
	v_fmac_f32_e32 v88, v76, v76
	v_fmac_f32_e32 v89, v77, v77
	v_fmac_f32_e32 v90, v78, v78
	v_fmac_f32_e32 v91, v79, v79
	v_add_f32_e32 v88, v88, v89
	v_add_f32_e32 v90, v90, v91
	v_add_f32_e32 v84, v88, v90
	s_nop 1
	v_add_f32_dpp v84, v84, v84 quad_perm:[1,0,3,2] row_mask:0xf bank_mask:0xf bound_ctrl:1
	s_nop 1
	v_add_f32_dpp v84, v84, v84 quad_perm:[2,3,0,1] row_mask:0xf bank_mask:0xf bound_ctrl:1
	s_nop 1
	v_add_f32_dpp v84, v84, v84 row_half_mirror row_mask:0xf bank_mask:0xf bound_ctrl:1
	s_nop 1
	v_add_f32_dpp v84, v84, v84 row_mirror row_mask:0xf bank_mask:0xf bound_ctrl:1
	s_nop 0
	v_readlane_b32 s44, v84, 0
	v_readlane_b32 s46, v84, 16
	v_readlane_b32 s48, v84, 32
	v_readlane_b32 s50, v84, 48
	s_nop 0
	v_mov_b32_e32 v85, s44
	v_mov_b32_e32 v86, s48
	v_add_f32_e32 v85, s46, v85
	v_add_f32_e32 v86, s50, v86
	v_add_f32_e32 v84, v85, v86
	v_fmamk_f32 v84, v84, 0x3a800000, v130
	v_rsq_f32_e32 v84, v84
	s_nop 0
	v_mul_f32_e32 v92, v84, v64
	v_fmac_f32_e32 v48, v0, v92
	v_mul_f32_e32 v93, v84, v65
	v_fmac_f32_e32 v49, v1, v93
	v_mul_f32_e32 v94, v84, v66
	v_fmac_f32_e32 v50, v2, v94
	v_mul_f32_e32 v95, v84, v67
	v_fmac_f32_e32 v51, v3, v95
	v_mul_f32_e32 v92, v84, v68
	v_fmac_f32_e32 v52, v4, v92
	v_mul_f32_e32 v93, v84, v69
	v_fmac_f32_e32 v53, v5, v93
	v_mul_f32_e32 v94, v84, v70
	v_fmac_f32_e32 v54, v6, v94
	v_mul_f32_e32 v95, v84, v71
	v_fmac_f32_e32 v55, v7, v95
	v_mul_f32_e32 v92, v84, v72
	v_fmac_f32_e32 v56, v8, v92
	v_mul_f32_e32 v93, v84, v73
	v_fmac_f32_e32 v57, v9, v93
	v_mul_f32_e32 v94, v84, v74
	v_fmac_f32_e32 v58, v10, v94
	v_mul_f32_e32 v95, v84, v75
	v_fmac_f32_e32 v59, v11, v95
	v_mul_f32_e32 v92, v84, v76
	v_fmac_f32_e32 v60, v12, v92
	v_mul_f32_e32 v93, v84, v77
	v_fmac_f32_e32 v61, v13, v93
	v_mul_f32_e32 v94, v84, v78
	v_fmac_f32_e32 v62, v14, v94
	v_mul_f32_e32 v95, v84, v79
	v_fmac_f32_e32 v63, v15, v95
	s_lshl_b32 s21, s20, 11
	s_cmp_lg_u32 s34, 0
	s_cbranch_scc1 .Lgro11_r3_fin
	s_add_u32 s22, s86, s21
	s_addc_u32 s23, s87, 0
	v_cvt_pk_bf16_f32 v100, v48, v49
	v_cvt_pk_bf16_f32 v101, v50, v51
	v_cvt_pk_bf16_f32 v102, v52, v53
	v_cvt_pk_bf16_f32 v103, v54, v55
	v_cvt_pk_bf16_f32 v104, v56, v57
	v_cvt_pk_bf16_f32 v105, v58, v59
	v_cvt_pk_bf16_f32 v106, v60, v61
	v_cvt_pk_bf16_f32 v107, v62, v63
	global_store_dwordx4 v82, v[100:103], s[22:23]
	global_store_dwordx4 v82, v[104:107], s[22:23] offset:1024
	v_mul_f32_e32 v88, v48, v48
	v_mul_f32_e32 v89, v49, v49
	v_mul_f32_e32 v90, v50, v50
	v_mul_f32_e32 v91, v51, v51
	v_fmac_f32_e32 v88, v52, v52
	v_fmac_f32_e32 v89, v53, v53
	v_fmac_f32_e32 v90, v54, v54
	v_fmac_f32_e32 v91, v55, v55
	v_fmac_f32_e32 v88, v56, v56
	v_fmac_f32_e32 v89, v57, v57
	v_fmac_f32_e32 v90, v58, v58
	v_fmac_f32_e32 v91, v59, v59
	v_fmac_f32_e32 v88, v60, v60
	v_fmac_f32_e32 v89, v61, v61
	v_fmac_f32_e32 v90, v62, v62
	v_fmac_f32_e32 v91, v63, v63
	v_add_f32_e32 v88, v88, v89
	v_add_f32_e32 v90, v90, v91
	v_add_f32_e32 v84, v88, v90
	s_nop 1
	v_add_f32_dpp v84, v84, v84 quad_perm:[1,0,3,2] row_mask:0xf bank_mask:0xf bound_ctrl:1
	s_nop 1
	v_add_f32_dpp v84, v84, v84 quad_perm:[2,3,0,1] row_mask:0xf bank_mask:0xf bound_ctrl:1
	s_nop 1
	v_add_f32_dpp v84, v84, v84 row_half_mirror row_mask:0xf bank_mask:0xf bound_ctrl:1
	s_nop 1
	v_add_f32_dpp v84, v84, v84 row_mirror row_mask:0xf bank_mask:0xf bound_ctrl:1
	s_nop 0
	v_readlane_b32 s44, v84, 0
	v_readlane_b32 s46, v84, 16
	v_readlane_b32 s48, v84, 32
	v_readlane_b32 s50, v84, 48
	s_nop 0
	v_mov_b32_e32 v85, s44
	v_mov_b32_e32 v86, s48
	v_add_f32_e32 v85, s46, v85
	v_add_f32_e32 v86, s50, v86
	v_add_f32_e32 v84, v85, v86
	v_fmamk_f32 v84, v84, 0x3a800000, v130
	v_rsq_f32_e32 v84, v84
	s_nop 0
	v_mul_f32_e32 v92, v48, v84
	v_fma_f32 v64, v92, v32, v16
	v_mul_f32_e32 v93, v49, v84
	v_fma_f32 v65, v93, v33, v17
	v_mul_f32_e32 v94, v50, v84
	v_fma_f32 v66, v94, v34, v18
	v_mul_f32_e32 v95, v51, v84
	v_fma_f32 v67, v95, v35, v19
	v_mul_f32_e32 v92, v52, v84
	v_fma_f32 v68, v92, v36, v20
	v_mul_f32_e32 v93, v53, v84
	v_fma_f32 v69, v93, v37, v21
	v_mul_f32_e32 v94, v54, v84
	v_fma_f32 v70, v94, v38, v22
	v_mul_f32_e32 v95, v55, v84
	v_fma_f32 v71, v95, v39, v23
	v_mul_f32_e32 v92, v56, v84
	v_fma_f32 v72, v92, v40, v24
	v_mul_f32_e32 v93, v57, v84
	v_fma_f32 v73, v93, v41, v25
	v_mul_f32_e32 v94, v58, v84
	v_fma_f32 v74, v94, v42, v26
	v_mul_f32_e32 v95, v59, v84
	v_fma_f32 v75, v95, v43, v27
	v_mul_f32_e32 v92, v60, v84
	v_fma_f32 v76, v92, v44, v28
	v_mul_f32_e32 v93, v61, v84
	v_fma_f32 v77, v93, v45, v29
	v_mul_f32_e32 v94, v62, v84
	v_fma_f32 v78, v94, v46, v30
	v_mul_f32_e32 v95, v63, v84
	v_fma_f32 v79, v95, v47, v31
	s_add_u32 s22, s18, s21
	s_addc_u32 s23, s19, 0
	v_cvt_pk_bf16_f32 v108, v64, v65
	v_cvt_pk_bf16_f32 v109, v66, v67
	v_cvt_pk_bf16_f32 v110, v68, v69
	v_cvt_pk_bf16_f32 v111, v70, v71
	v_cvt_pk_bf16_f32 v112, v72, v73
	v_cvt_pk_bf16_f32 v113, v74, v75
	v_cvt_pk_bf16_f32 v114, v76, v77
	v_cvt_pk_bf16_f32 v115, v78, v79
	global_store_dwordx4 v82, v[108:111], s[22:23]
	global_store_dwordx4 v82, v[112:115], s[22:23] offset:1024
	s_branch .Lgro11_r3_done

.Lgro11_r4_go:
	v_lshlrev_b32_e32 v48, 16, v232
	v_and_b32_e32 v49, 0xffff0000, v232
	v_lshlrev_b32_e32 v50, 16, v233
	v_and_b32_e32 v51, 0xffff0000, v233
	v_lshlrev_b32_e32 v52, 16, v234
	v_and_b32_e32 v53, 0xffff0000, v234
	v_lshlrev_b32_e32 v54, 16, v235
	v_and_b32_e32 v55, 0xffff0000, v235
	v_lshlrev_b32_e32 v56, 16, v236
	v_and_b32_e32 v57, 0xffff0000, v236
	v_lshlrev_b32_e32 v58, 16, v237
	v_and_b32_e32 v59, 0xffff0000, v237
	v_lshlrev_b32_e32 v60, 16, v238
	v_and_b32_e32 v61, 0xffff0000, v238
	v_lshlrev_b32_e32 v62, 16, v239
	v_and_b32_e32 v63, 0xffff0000, v239
	v_lshlrev_b32_e32 v64, 16, v240
	v_and_b32_e32 v65, 0xffff0000, v240
	v_lshlrev_b32_e32 v66, 16, v241
	v_and_b32_e32 v67, 0xffff0000, v241
	v_lshlrev_b32_e32 v68, 16, v242
	v_and_b32_e32 v69, 0xffff0000, v242
	v_lshlrev_b32_e32 v70, 16, v243
	v_and_b32_e32 v71, 0xffff0000, v243
	v_lshlrev_b32_e32 v72, 16, v244
	v_and_b32_e32 v73, 0xffff0000, v244
	v_lshlrev_b32_e32 v74, 16, v245
	v_and_b32_e32 v75, 0xffff0000, v245
	v_lshlrev_b32_e32 v76, 16, v246
	v_and_b32_e32 v77, 0xffff0000, v246
	v_lshlrev_b32_e32 v78, 16, v247
	v_and_b32_e32 v79, 0xffff0000, v247
	v_mul_f32_e32 v88, v64, v64
	v_mul_f32_e32 v89, v65, v65
	v_mul_f32_e32 v90, v66, v66
	v_mul_f32_e32 v91, v67, v67
	v_fmac_f32_e32 v88, v68, v68
	v_fmac_f32_e32 v89, v69, v69
	v_fmac_f32_e32 v90, v70, v70
	v_fmac_f32_e32 v91, v71, v71
	v_fmac_f32_e32 v88, v72, v72
	v_fmac_f32_e32 v89, v73, v73
	v_fmac_f32_e32 v90, v74, v74
	v_fmac_f32_e32 v91, v75, v75
	v_fmac_f32_e32 v88, v76, v76
	v_fmac_f32_e32 v89, v77, v77
	v_fmac_f32_e32 v90, v78, v78
	v_fmac_f32_e32 v91, v79, v79
	v_add_f32_e32 v88, v88, v89
	v_add_f32_e32 v90, v90, v91
	v_add_f32_e32 v84, v88, v90
	s_nop 1
	v_add_f32_dpp v84, v84, v84 quad_perm:[1,0,3,2] row_mask:0xf bank_mask:0xf bound_ctrl:1
	s_nop 1
	v_add_f32_dpp v84, v84, v84 quad_perm:[2,3,0,1] row_mask:0xf bank_mask:0xf bound_ctrl:1
	s_nop 1
	v_add_f32_dpp v84, v84, v84 row_half_mirror row_mask:0xf bank_mask:0xf bound_ctrl:1
	s_nop 1
	v_add_f32_dpp v84, v84, v84 row_mirror row_mask:0xf bank_mask:0xf bound_ctrl:1
	s_nop 0
	v_readlane_b32 s44, v84, 0
	v_readlane_b32 s46, v84, 16
	v_readlane_b32 s48, v84, 32
	v_readlane_b32 s50, v84, 48
	s_nop 0
	v_mov_b32_e32 v85, s44
	v_mov_b32_e32 v86, s48
	v_add_f32_e32 v85, s46, v85
	v_add_f32_e32 v86, s50, v86
	v_add_f32_e32 v84, v85, v86
	v_fmamk_f32 v84, v84, 0x3a800000, v130
	v_rsq_f32_e32 v84, v84
	s_nop 0
	v_mul_f32_e32 v92, v84, v64
	v_fmac_f32_e32 v48, v0, v92
	v_mul_f32_e32 v93, v84, v65
	v_fmac_f32_e32 v49, v1, v93
	v_mul_f32_e32 v94, v84, v66
	v_fmac_f32_e32 v50, v2, v94
	v_mul_f32_e32 v95, v84, v67
	v_fmac_f32_e32 v51, v3, v95
	v_mul_f32_e32 v92, v84, v68
	v_fmac_f32_e32 v52, v4, v92
	v_mul_f32_e32 v93, v84, v69
	v_fmac_f32_e32 v53, v5, v93
	v_mul_f32_e32 v94, v84, v70
	v_fmac_f32_e32 v54, v6, v94
	v_mul_f32_e32 v95, v84, v71
	v_fmac_f32_e32 v55, v7, v95
	v_mul_f32_e32 v92, v84, v72
	v_fmac_f32_e32 v56, v8, v92
	v_mul_f32_e32 v93, v84, v73
	v_fmac_f32_e32 v57, v9, v93
	v_mul_f32_e32 v94, v84, v74
	v_fmac_f32_e32 v58, v10, v94
	v_mul_f32_e32 v95, v84, v75
	v_fmac_f32_e32 v59, v11, v95
	v_mul_f32_e32 v92, v84, v76
	v_fmac_f32_e32 v60, v12, v92
	v_mul_f32_e32 v93, v84, v77
	v_fmac_f32_e32 v61, v13, v93
	v_mul_f32_e32 v94, v84, v78
	v_fmac_f32_e32 v62, v14, v94
	v_mul_f32_e32 v95, v84, v79
	v_fmac_f32_e32 v63, v15, v95
	s_lshl_b32 s21, s20, 11
	s_cmp_lg_u32 s34, 0
	s_cbranch_scc1 .Lgro11_r4_fin
	s_add_u32 s22, s86, s21
	s_addc_u32 s23, s87, 0
	v_cvt_pk_bf16_f32 v100, v48, v49
	v_cvt_pk_bf16_f32 v101, v50, v51
	v_cvt_pk_bf16_f32 v102, v52, v53
	v_cvt_pk_bf16_f32 v103, v54, v55
	v_cvt_pk_bf16_f32 v104, v56, v57
	v_cvt_pk_bf16_f32 v105, v58, v59
	v_cvt_pk_bf16_f32 v106, v60, v61
	v_cvt_pk_bf16_f32 v107, v62, v63
	global_store_dwordx4 v82, v[100:103], s[22:23]
	global_store_dwordx4 v82, v[104:107], s[22:23] offset:1024
	v_mul_f32_e32 v88, v48, v48
	v_mul_f32_e32 v89, v49, v49
	v_mul_f32_e32 v90, v50, v50
	v_mul_f32_e32 v91, v51, v51
	v_fmac_f32_e32 v88, v52, v52
	v_fmac_f32_e32 v89, v53, v53
	v_fmac_f32_e32 v90, v54, v54
	v_fmac_f32_e32 v91, v55, v55
	v_fmac_f32_e32 v88, v56, v56
	v_fmac_f32_e32 v89, v57, v57
	v_fmac_f32_e32 v90, v58, v58
	v_fmac_f32_e32 v91, v59, v59
	v_fmac_f32_e32 v88, v60, v60
	v_fmac_f32_e32 v89, v61, v61
	v_fmac_f32_e32 v90, v62, v62
	v_fmac_f32_e32 v91, v63, v63
	v_add_f32_e32 v88, v88, v89
	v_add_f32_e32 v90, v90, v91
	v_add_f32_e32 v84, v88, v90
	s_nop 1
	v_add_f32_dpp v84, v84, v84 quad_perm:[1,0,3,2] row_mask:0xf bank_mask:0xf bound_ctrl:1
	s_nop 1
	v_add_f32_dpp v84, v84, v84 quad_perm:[2,3,0,1] row_mask:0xf bank_mask:0xf bound_ctrl:1
	s_nop 1
	v_add_f32_dpp v84, v84, v84 row_half_mirror row_mask:0xf bank_mask:0xf bound_ctrl:1
	s_nop 1
	v_add_f32_dpp v84, v84, v84 row_mirror row_mask:0xf bank_mask:0xf bound_ctrl:1
	s_nop 0
	v_readlane_b32 s44, v84, 0
	v_readlane_b32 s46, v84, 16
	v_readlane_b32 s48, v84, 32
	v_readlane_b32 s50, v84, 48
	s_nop 0
	v_mov_b32_e32 v85, s44
	v_mov_b32_e32 v86, s48
	v_add_f32_e32 v85, s46, v85
	v_add_f32_e32 v86, s50, v86
	v_add_f32_e32 v84, v85, v86
	v_fmamk_f32 v84, v84, 0x3a800000, v130
	v_rsq_f32_e32 v84, v84
	s_nop 0
	v_mul_f32_e32 v92, v48, v84
	v_fma_f32 v64, v92, v32, v16
	v_mul_f32_e32 v93, v49, v84
	v_fma_f32 v65, v93, v33, v17
	v_mul_f32_e32 v94, v50, v84
	v_fma_f32 v66, v94, v34, v18
	v_mul_f32_e32 v95, v51, v84
	v_fma_f32 v67, v95, v35, v19
	v_mul_f32_e32 v92, v52, v84
	v_fma_f32 v68, v92, v36, v20
	v_mul_f32_e32 v93, v53, v84
	v_fma_f32 v69, v93, v37, v21
	v_mul_f32_e32 v94, v54, v84
	v_fma_f32 v70, v94, v38, v22
	v_mul_f32_e32 v95, v55, v84
	v_fma_f32 v71, v95, v39, v23
	v_mul_f32_e32 v92, v56, v84
	v_fma_f32 v72, v92, v40, v24
	v_mul_f32_e32 v93, v57, v84
	v_fma_f32 v73, v93, v41, v25
	v_mul_f32_e32 v94, v58, v84
	v_fma_f32 v74, v94, v42, v26
	v_mul_f32_e32 v95, v59, v84
	v_fma_f32 v75, v95, v43, v27
	v_mul_f32_e32 v92, v60, v84
	v_fma_f32 v76, v92, v44, v28
	v_mul_f32_e32 v93, v61, v84
	v_fma_f32 v77, v93, v45, v29
	v_mul_f32_e32 v94, v62, v84
	v_fma_f32 v78, v94, v46, v30
	v_mul_f32_e32 v95, v63, v84
	v_fma_f32 v79, v95, v47, v31
	s_add_u32 s22, s18, s21
	s_addc_u32 s23, s19, 0
	v_cvt_pk_bf16_f32 v108, v64, v65
	v_cvt_pk_bf16_f32 v109, v66, v67
	v_cvt_pk_bf16_f32 v110, v68, v69
	v_cvt_pk_bf16_f32 v111, v70, v71
	v_cvt_pk_bf16_f32 v112, v72, v73
	v_cvt_pk_bf16_f32 v113, v74, v75
	v_cvt_pk_bf16_f32 v114, v76, v77
	v_cvt_pk_bf16_f32 v115, v78, v79
	global_store_dwordx4 v82, v[108:111], s[22:23]
	global_store_dwordx4 v82, v[112:115], s[22:23] offset:1024
	s_branch .Lgro11_r4_done

.Lgro11_r4_done:
.Lgro11_bend:
	s_mul_i32 s4, s14, 5
	s_add_u32 s13, s13, s4
	s_cmp_lt_u32 s13, 0x2800
	s_cbranch_scc1 .Lgro11_batch
